# v91 + mout readout: norm-weight loads of column blocks 1..4 hoisted out of the per-quad chain
# speedup vs baseline: 1.0038x; 1.0037x over previous
.LBB1_99:
	v_mul_f32_e32 v116, v33, v35
	v_cvt_pk_bf16_f32 v32, v32, v36
	v_cvt_pk_bf16_f32 v33, v41, v38
	ds_write_b64 v43, v[32:33] offset:4576
	v_add_u32_e32 v56, v158, v42
	v_mul_f32_e32 v110, v45, v47
	v_mul_f32_e32 v114, v44, v46
	v_mul_f32_e32 v112, v34, v37
	s_waitcnt lgkmcnt(0)
	s_barrier
	ds_read_b128 v[32:35], v56
	ds_read_b128 v[36:39], v56 offset:64
	ds_read_b128 v[40:43], v56 offset:128
	ds_read_b128 v[88:91], v56 offset:192
	ds_read_b128 v[44:47], v56 offset:4352
	ds_read_b128 v[48:51], v56 offset:4416
	ds_read_b128 v[52:55], v56 offset:4480
	ds_read_b128 v[92:95], v56 offset:4544
	ds_read_b128 v[56:59], v157 offset:34816
	ds_read_b128 v[60:63], v157 offset:39168
	ds_read_b128 v[64:67], v157 offset:43520
	ds_read_b128 v[68:71], v157 offset:47872
	ds_read_b128 v[72:75], v157 offset:52224
	ds_read_b128 v[76:79], v157 offset:56576
	ds_read_b128 v[80:83], v157 offset:60928
	ds_read_b128 v[84:87], v157 offset:65280
	s_setprio 1
	s_waitcnt lgkmcnt(7)
	v_mfma_f32_16x16x32_bf16 v[96:99], v[56:59], v[32:35], 0
	v_mfma_f32_16x16x32_bf16 v[56:59], v[56:59], v[44:47], 0
	s_waitcnt lgkmcnt(6)
	v_mfma_f32_16x16x32_bf16 v[100:103], v[60:63], v[32:35], 0
	v_mfma_f32_16x16x32_bf16 v[60:63], v[60:63], v[44:47], 0
	s_waitcnt lgkmcnt(5)
	v_mfma_f32_16x16x32_bf16 v[118:121], v[64:67], v[32:35], 0
	v_mfma_f32_16x16x32_bf16 v[64:67], v[64:67], v[44:47], 0
	s_waitcnt lgkmcnt(4)
	v_mfma_f32_16x16x32_bf16 v[122:125], v[68:71], v[32:35], 0
	v_mfma_f32_16x16x32_bf16 v[68:71], v[68:71], v[44:47], 0
	s_waitcnt lgkmcnt(3)
	v_mfma_f32_16x16x32_bf16 v[130:133], v[72:75], v[32:35], 0
	v_mfma_f32_16x16x32_bf16 v[72:75], v[72:75], v[44:47], 0
	s_waitcnt lgkmcnt(2)
	v_mfma_f32_16x16x32_bf16 v[134:137], v[76:79], v[32:35], 0
	v_mfma_f32_16x16x32_bf16 v[76:79], v[76:79], v[44:47], 0
	s_waitcnt lgkmcnt(1)
	v_mfma_f32_16x16x32_bf16 v[138:141], v[80:83], v[32:35], 0
	v_mfma_f32_16x16x32_bf16 v[80:83], v[80:83], v[44:47], 0
	s_waitcnt lgkmcnt(0)
	v_mfma_f32_16x16x32_bf16 v[32:35], v[84:87], v[32:35], 0
	v_mfma_f32_16x16x32_bf16 v[44:47], v[84:87], v[44:47], 0
	s_setprio 0
	ds_read_b128 v[84:87], v157 offset:34880
	ds_read_b128 v[142:145], v157 offset:39232
	ds_read_b128 v[146:149], v157 offset:43584
	ds_read_b128 v[150:153], v157 offset:47936
	ds_read_b128 v[158:161], v157 offset:52288
	ds_read_b128 v[188:191], v157 offset:56640
	ds_read_b128 v[192:195], v157 offset:60992
	ds_read_b128 v[196:199], v157 offset:65344
	s_setprio 1
	s_waitcnt lgkmcnt(7)
	v_mfma_f32_16x16x32_bf16 v[96:99], v[84:87], v[36:39], v[96:99]
	v_mfma_f32_16x16x32_bf16 v[56:59], v[84:87], v[48:51], v[56:59]
	s_waitcnt lgkmcnt(6)
	v_mfma_f32_16x16x32_bf16 v[84:87], v[142:145], v[36:39], v[100:103]
	v_mfma_f32_16x16x32_bf16 v[60:63], v[142:145], v[48:51], v[60:63]
	s_waitcnt lgkmcnt(5)
	v_mfma_f32_16x16x32_bf16 v[100:103], v[146:149], v[36:39], v[118:121]
	v_mfma_f32_16x16x32_bf16 v[64:67], v[146:149], v[48:51], v[64:67]
	s_waitcnt lgkmcnt(4)
	v_mfma_f32_16x16x32_bf16 v[118:121], v[150:153], v[36:39], v[122:125]
	v_mfma_f32_16x16x32_bf16 v[68:71], v[150:153], v[48:51], v[68:71]
	s_waitcnt lgkmcnt(3)
	v_mfma_f32_16x16x32_bf16 v[122:125], v[158:161], v[36:39], v[130:133]
	v_mfma_f32_16x16x32_bf16 v[72:75], v[158:161], v[48:51], v[72:75]
	s_waitcnt lgkmcnt(2)
	v_mfma_f32_16x16x32_bf16 v[130:133], v[188:191], v[36:39], v[134:137]
	v_mfma_f32_16x16x32_bf16 v[76:79], v[188:191], v[48:51], v[76:79]
	s_waitcnt lgkmcnt(1)
	v_mfma_f32_16x16x32_bf16 v[134:137], v[192:195], v[36:39], v[138:141]
	v_mfma_f32_16x16x32_bf16 v[80:83], v[192:195], v[48:51], v[80:83]
	s_waitcnt lgkmcnt(0)
	v_mfma_f32_16x16x32_bf16 v[32:35], v[196:199], v[36:39], v[32:35]
	v_mfma_f32_16x16x32_bf16 v[36:39], v[196:199], v[48:51], v[44:47]
	s_setprio 0
	s_nop 1
	ds_read_b128 v[44:47], v157 offset:34944
	ds_read_b128 v[48:51], v157 offset:39296
	ds_read_b128 v[138:141], v157 offset:43648
	ds_read_b128 v[142:145], v157 offset:48000
	ds_read_b128 v[146:149], v157 offset:52352
	ds_read_b128 v[150:153], v157 offset:56704
	ds_read_b128 v[158:161], v157 offset:61056
	ds_read_b128 v[188:191], v157 offset:65408
	s_setprio 1
	s_waitcnt lgkmcnt(7)
	v_mfma_f32_16x16x32_bf16 v[96:99], v[44:47], v[40:43], v[96:99]
	v_mfma_f32_16x16x32_bf16 v[44:47], v[44:47], v[52:55], v[56:59]
	s_waitcnt lgkmcnt(6)
	v_mfma_f32_16x16x32_bf16 v[56:59], v[48:51], v[40:43], v[84:87]
	v_mfma_f32_16x16x32_bf16 v[48:51], v[48:51], v[52:55], v[60:63]
	s_waitcnt lgkmcnt(5)
	v_mfma_f32_16x16x32_bf16 v[60:63], v[138:141], v[40:43], v[100:103]
	v_mfma_f32_16x16x32_bf16 v[64:67], v[138:141], v[52:55], v[64:67]
	s_waitcnt lgkmcnt(4)
	v_mfma_f32_16x16x32_bf16 v[84:87], v[142:145], v[40:43], v[118:121]
	v_mfma_f32_16x16x32_bf16 v[68:71], v[142:145], v[52:55], v[68:71]
	s_waitcnt lgkmcnt(3)
	v_mfma_f32_16x16x32_bf16 v[100:103], v[146:149], v[40:43], v[122:125]
	v_mfma_f32_16x16x32_bf16 v[72:75], v[146:149], v[52:55], v[72:75]
	s_waitcnt lgkmcnt(2)
	v_mfma_f32_16x16x32_bf16 v[118:121], v[150:153], v[40:43], v[130:133]
	v_mfma_f32_16x16x32_bf16 v[76:79], v[150:153], v[52:55], v[76:79]
	s_waitcnt lgkmcnt(1)
	v_mfma_f32_16x16x32_bf16 v[122:125], v[158:161], v[40:43], v[134:137]
	v_mfma_f32_16x16x32_bf16 v[130:133], v[158:161], v[52:55], v[80:83]
	s_waitcnt lgkmcnt(0)
	v_mfma_f32_16x16x32_bf16 v[134:137], v[188:191], v[40:43], v[32:35]
	v_mfma_f32_16x16x32_bf16 v[138:141], v[188:191], v[52:55], v[36:39]
	s_setprio 0
	s_nop 1
	ds_read_b128 v[36:39], v157 offset:35008
	ds_read_b128 v[52:55], v157 offset:39360
	ds_read_b128 v[80:83], v157 offset:43712
	ds_read_b128 v[142:145], v157 offset:48064
	ds_read_b128 v[146:149], v157 offset:52416
	ds_read_b128 v[150:153], v157 offset:56768
	ds_read_b128 v[158:161], v157 offset:61120
	ds_read_b128 v[188:191], v157 offset:65472
	s_setprio 1
	s_waitcnt lgkmcnt(7)
	v_mfma_f32_16x16x32_bf16 v[32:35], v[36:39], v[88:91], v[96:99]
	v_mfma_f32_16x16x32_bf16 v[36:39], v[36:39], v[92:95], v[44:47]
	s_waitcnt lgkmcnt(6)
	v_mfma_f32_16x16x32_bf16 v[40:43], v[52:55], v[88:91], v[56:59]
	v_mfma_f32_16x16x32_bf16 v[44:47], v[52:55], v[92:95], v[48:51]
	s_waitcnt lgkmcnt(5)
	v_mfma_f32_16x16x32_bf16 v[48:51], v[80:83], v[88:91], v[60:63]
	v_mfma_f32_16x16x32_bf16 v[52:55], v[80:83], v[92:95], v[64:67]
	s_waitcnt lgkmcnt(4)
	v_mfma_f32_16x16x32_bf16 v[56:59], v[142:145], v[88:91], v[84:87]
	v_mfma_f32_16x16x32_bf16 v[60:63], v[142:145], v[92:95], v[68:71]
	s_waitcnt lgkmcnt(3)
	v_mfma_f32_16x16x32_bf16 v[64:67], v[146:149], v[88:91], v[100:103]
	v_mfma_f32_16x16x32_bf16 v[68:71], v[146:149], v[92:95], v[72:75]
	s_waitcnt lgkmcnt(2)
	v_mfma_f32_16x16x32_bf16 v[72:75], v[150:153], v[88:91], v[118:121]
	v_mfma_f32_16x16x32_bf16 v[76:79], v[150:153], v[92:95], v[76:79]
	s_waitcnt lgkmcnt(1)
	v_mfma_f32_16x16x32_bf16 v[80:83], v[158:161], v[88:91], v[122:125]
	v_mfma_f32_16x16x32_bf16 v[84:87], v[158:161], v[92:95], v[130:133]
	s_waitcnt lgkmcnt(0)
	v_mfma_f32_16x16x32_bf16 v[88:91], v[188:191], v[88:91], v[134:137]
	v_mfma_f32_16x16x32_bf16 v[92:95], v[188:191], v[92:95], v[138:141]
	s_setprio 0
	s_lshl_b64 s[4:5], s[70:71], 15
	s_add_u32 s4, s80, s4
	s_addc_u32 s5, s81, s5
	v_lshlrev_b64 v[96:97], 8, v[104:105]
	v_lshl_add_u64 v[98:99], s[4:5], 0, v[96:97]
	s_lshl_b64 s[4:5], s[68:69], 15
	s_add_u32 s4, s80, s4
	s_addc_u32 s5, s81, s5
	v_lshl_add_u64 v[100:101], v[98:99], 0, v[128:129]
	v_lshl_add_u64 v[96:97], s[4:5], 0, v[96:97]
	s_barrier
	v_lshl_add_u64 v[102:103], v[96:97], 0, v[128:129]
	global_load_dwordx4 v[204:207], v[100:101], off
	s_movk_i32 s5, 0x2000
	v_add_co_u32_e32 v104, vcc, s5, v100
	s_movk_i32 s2, 0x4000
	s_nop 0
	v_addc_co_u32_e32 v105, vcc, 0, v101, vcc
	s_movk_i32 s4, 0x6000
	s_movk_i32 s6, 0x7000
	v_mov_b64_e32 v[132:133], v[10:11]
	v_mov_b64_e32 v[130:131], v[8:9]
	v_mov_b64_e32 v[136:137], v[6:7]
	v_mov_b64_e32 v[134:135], v[4:5]
	v_mov_b64_e32 v[140:141], v[2:3]
	v_mov_b64_e32 v[138:139], v[0:1]
	global_load_dwordx4 v[208:211], v[104:105], off offset:-4096
	global_load_dwordx4 v[216:219], v[104:105], off
	v_add_co_u32_e32 v104, vcc, s2, v100
	v_addc_co_u32_e32 v105, vcc, 0, v101, vcc
	global_load_dwordx4 v[220:223], v[104:105], off offset:-4096
	global_load_dwordx4 v[224:227], v[104:105], off
	v_add_co_u32_e32 v104, vcc, s4, v100
	v_addc_co_u32_e32 v105, vcc, 0, v101, vcc
	global_load_dwordx4 v[228:231], v[104:105], off offset:-4096
	global_load_dwordx4 v[232:235], v[104:105], off
	v_add_co_u32_e32 v96, vcc, s6, v100
	s_nop 1
	v_addc_co_u32_e32 v97, vcc, 0, v101, vcc
	global_load_dwordx4 v[236:239], v[96:97], off
	s_waitcnt vmcnt(0)
	ds_write_b128 v107, v[204:207]
	ds_write_b128 v107, v[208:211] offset:4352
	ds_write_b128 v107, v[216:219] offset:8704
	ds_write_b128 v107, v[220:223] offset:13056
	ds_write_b128 v107, v[224:227] offset:17408
	ds_write_b128 v107, v[228:231] offset:21760
	ds_write_b128 v107, v[232:235] offset:26112
	ds_write_b128 v107, v[236:239] offset:30464
	v_add_co_u32_e32 v100, vcc, s5, v102
	global_load_dwordx4 v[204:207], v[102:103], off
	v_addc_co_u32_e32 v101, vcc, 0, v103, vcc
	global_load_dwordx4 v[208:211], v[100:101], off offset:-4096
	global_load_dwordx4 v[216:219], v[100:101], off
	v_add_co_u32_e32 v100, vcc, s2, v102
	v_addc_co_u32_e32 v101, vcc, 0, v103, vcc
	global_load_dwordx4 v[220:223], v[100:101], off offset:-4096
	global_load_dwordx4 v[224:227], v[100:101], off
	v_add_co_u32_e32 v100, vcc, s4, v102
	v_addc_co_u32_e32 v101, vcc, 0, v103, vcc
	global_load_dwordx4 v[228:231], v[100:101], off offset:-4096
	global_load_dwordx4 v[232:235], v[100:101], off
	v_add_co_u32_e32 v96, vcc, s6, v102
	s_nop 1
	v_addc_co_u32_e32 v97, vcc, 0, v103, vcc
	global_load_dwordx4 v[236:239], v[96:97], off
	s_waitcnt vmcnt(0)
	ds_write_b128 v107, v[204:207] offset:34816
	ds_write_b128 v107, v[208:211] offset:39168
	ds_write_b128 v107, v[216:219] offset:43520
	ds_write_b128 v107, v[220:223] offset:47872
	ds_write_b128 v107, v[224:227] offset:52224
	ds_write_b128 v107, v[228:231] offset:56576
	ds_write_b128 v107, v[232:235] offset:60928
	ds_write_b128 v107, v[236:239] offset:65280
	v_mov_b64_e32 v[98:99], v[30:31]
	v_mov_b64_e32 v[96:97], v[28:29]
	s_waitcnt lgkmcnt(0)
	s_barrier
	s_nop 0
	v_lshlrev_b32_e32 v100, 16, v96
	v_and_b32_e32 v101, 0xffff0000, v96
	v_pk_mul_f32 v[100:101], v[116:117], v[100:101] op_sel_hi:[0,1]
	v_cvt_pk_bf16_f32 v96, v100, v101
	v_lshlrev_b32_e32 v100, 16, v97
	v_and_b32_e32 v101, 0xffff0000, v97
	v_pk_mul_f32 v[100:101], v[116:117], v[100:101] op_sel_hi:[0,1]
	v_cvt_pk_bf16_f32 v97, v100, v101
	v_lshlrev_b32_e32 v100, 16, v98
	v_and_b32_e32 v101, 0xffff0000, v98
	v_pk_mul_f32 v[100:101], v[116:117], v[100:101] op_sel_hi:[0,1]
	v_cvt_pk_bf16_f32 v98, v100, v101
	v_lshlrev_b32_e32 v100, 16, v99
	v_and_b32_e32 v101, 0xffff0000, v99
	v_pk_mul_f32 v[100:101], v[116:117], v[100:101] op_sel_hi:[0,1]
	v_cvt_pk_bf16_f32 v99, v100, v101
	v_mov_b64_e32 v[102:103], v[26:27]
	v_mov_b64_e32 v[100:101], v[24:25]
	s_nop 0
	v_lshlrev_b32_e32 v104, 16, v100
	v_and_b32_e32 v105, 0xffff0000, v100
	v_pk_mul_f32 v[104:105], v[114:115], v[104:105] op_sel_hi:[0,1]
	v_cvt_pk_bf16_f32 v100, v104, v105
	v_lshlrev_b32_e32 v104, 16, v101
	v_and_b32_e32 v105, 0xffff0000, v101
	v_pk_mul_f32 v[104:105], v[114:115], v[104:105] op_sel_hi:[0,1]
	v_cvt_pk_bf16_f32 v101, v104, v105
	v_lshlrev_b32_e32 v104, 16, v102
	v_and_b32_e32 v105, 0xffff0000, v102
	v_pk_mul_f32 v[104:105], v[114:115], v[104:105] op_sel_hi:[0,1]
	v_cvt_pk_bf16_f32 v102, v104, v105
	v_lshlrev_b32_e32 v104, 16, v103
	v_and_b32_e32 v105, 0xffff0000, v103
	v_pk_mul_f32 v[104:105], v[114:115], v[104:105] op_sel_hi:[0,1]
	v_cvt_pk_bf16_f32 v103, v104, v105
	v_mov_b64_e32 v[106:107], v[22:23]
	v_mov_b64_e32 v[104:105], v[20:21]
	s_nop 0
	v_lshlrev_b32_e32 v118, 16, v104
	v_and_b32_e32 v119, 0xffff0000, v104
	v_pk_mul_f32 v[118:119], v[116:117], v[118:119] op_sel_hi:[0,1]
	v_cvt_pk_bf16_f32 v104, v118, v119
	v_lshlrev_b32_e32 v118, 16, v105
	v_and_b32_e32 v119, 0xffff0000, v105
	v_pk_mul_f32 v[118:119], v[116:117], v[118:119] op_sel_hi:[0,1]
	v_cvt_pk_bf16_f32 v105, v118, v119
	v_lshlrev_b32_e32 v118, 16, v106
	v_and_b32_e32 v119, 0xffff0000, v106
	v_pk_mul_f32 v[118:119], v[116:117], v[118:119] op_sel_hi:[0,1]
	v_cvt_pk_bf16_f32 v106, v118, v119
	v_lshlrev_b32_e32 v118, 16, v107
	v_and_b32_e32 v119, 0xffff0000, v107
	v_pk_mul_f32 v[118:119], v[116:117], v[118:119] op_sel_hi:[0,1]
	v_cvt_pk_bf16_f32 v107, v118, v119
	v_mov_b64_e32 v[120:121], v[18:19]
	v_mov_b64_e32 v[118:119], v[16:17]
	s_nop 0
	v_lshlrev_b32_e32 v122, 16, v118
	v_and_b32_e32 v123, 0xffff0000, v118
	v_pk_mul_f32 v[122:123], v[114:115], v[122:123] op_sel_hi:[0,1]
	v_cvt_pk_bf16_f32 v118, v122, v123
	v_lshlrev_b32_e32 v122, 16, v119
	v_and_b32_e32 v123, 0xffff0000, v119
	v_pk_mul_f32 v[122:123], v[114:115], v[122:123] op_sel_hi:[0,1]
	v_cvt_pk_bf16_f32 v119, v122, v123
	v_lshlrev_b32_e32 v122, 16, v120
	v_and_b32_e32 v123, 0xffff0000, v120
	v_pk_mul_f32 v[122:123], v[114:115], v[122:123] op_sel_hi:[0,1]
	v_cvt_pk_bf16_f32 v120, v122, v123
	v_lshlrev_b32_e32 v122, 16, v121
	v_and_b32_e32 v123, 0xffff0000, v121
	v_pk_mul_f32 v[122:123], v[114:115], v[122:123] op_sel_hi:[0,1]
	v_cvt_pk_bf16_f32 v121, v122, v123
	v_mov_b64_e32 v[124:125], v[14:15]
	v_mov_b64_e32 v[122:123], v[12:13]
	s_nop 0
	v_lshlrev_b32_e32 v126, 16, v122
	v_and_b32_e32 v127, 0xffff0000, v122
	v_pk_mul_f32 v[126:127], v[116:117], v[126:127] op_sel_hi:[0,1]
	v_cvt_pk_bf16_f32 v122, v126, v127
	v_lshlrev_b32_e32 v126, 16, v123
	v_and_b32_e32 v127, 0xffff0000, v123
	v_pk_mul_f32 v[126:127], v[116:117], v[126:127] op_sel_hi:[0,1]
	v_cvt_pk_bf16_f32 v123, v126, v127
	v_lshlrev_b32_e32 v126, 16, v124
	v_and_b32_e32 v127, 0xffff0000, v124
	v_pk_mul_f32 v[126:127], v[116:117], v[126:127] op_sel_hi:[0,1]
	v_cvt_pk_bf16_f32 v124, v126, v127
	v_lshlrev_b32_e32 v126, 16, v125
	v_and_b32_e32 v127, 0xffff0000, v125
	v_pk_mul_f32 v[126:127], v[116:117], v[126:127] op_sel_hi:[0,1]
	v_cvt_pk_bf16_f32 v125, v126, v127
	v_lshlrev_b32_e32 v126, 16, v130
	v_and_b32_e32 v127, 0xffff0000, v130
	v_pk_mul_f32 v[126:127], v[114:115], v[126:127] op_sel_hi:[0,1]
	v_cvt_pk_bf16_f32 v130, v126, v127
	v_lshlrev_b32_e32 v126, 16, v131
	v_and_b32_e32 v127, 0xffff0000, v131
	v_pk_mul_f32 v[126:127], v[114:115], v[126:127] op_sel_hi:[0,1]
	v_cvt_pk_bf16_f32 v131, v126, v127
	v_lshlrev_b32_e32 v126, 16, v132
	v_and_b32_e32 v127, 0xffff0000, v132
	v_pk_mul_f32 v[126:127], v[114:115], v[126:127] op_sel_hi:[0,1]
	v_cvt_pk_bf16_f32 v132, v126, v127
	v_lshlrev_b32_e32 v126, 16, v133
	v_and_b32_e32 v127, 0xffff0000, v133
	v_pk_mul_f32 v[126:127], v[114:115], v[126:127] op_sel_hi:[0,1]
	v_cvt_pk_bf16_f32 v133, v126, v127
	v_lshlrev_b32_e32 v126, 16, v134
	v_and_b32_e32 v127, 0xffff0000, v134
	v_pk_mul_f32 v[126:127], v[116:117], v[126:127] op_sel_hi:[0,1]
	v_cvt_pk_bf16_f32 v134, v126, v127
	v_lshlrev_b32_e32 v126, 16, v135
	v_and_b32_e32 v127, 0xffff0000, v135
	v_pk_mul_f32 v[126:127], v[116:117], v[126:127] op_sel_hi:[0,1]
	v_cvt_pk_bf16_f32 v135, v126, v127
	v_lshlrev_b32_e32 v126, 16, v136
	v_and_b32_e32 v127, 0xffff0000, v136
	v_pk_mul_f32 v[126:127], v[116:117], v[126:127] op_sel_hi:[0,1]
	v_cvt_pk_bf16_f32 v136, v126, v127
	v_lshlrev_b32_e32 v126, 16, v137
	v_and_b32_e32 v127, 0xffff0000, v137
	v_pk_mul_f32 v[116:117], v[116:117], v[126:127] op_sel_hi:[0,1]
	v_cvt_pk_bf16_f32 v137, v116, v117
	v_lshlrev_b32_e32 v116, 16, v138
	v_and_b32_e32 v117, 0xffff0000, v138
	v_pk_mul_f32 v[116:117], v[114:115], v[116:117] op_sel_hi:[0,1]
	v_cvt_pk_bf16_f32 v138, v116, v117
	v_lshlrev_b32_e32 v116, 16, v139
	v_and_b32_e32 v117, 0xffff0000, v139
	v_pk_mul_f32 v[116:117], v[114:115], v[116:117] op_sel_hi:[0,1]
	v_cvt_pk_bf16_f32 v139, v116, v117
	v_lshlrev_b32_e32 v116, 16, v140
	v_and_b32_e32 v117, 0xffff0000, v140
	v_pk_mul_f32 v[116:117], v[114:115], v[116:117] op_sel_hi:[0,1]
	v_cvt_pk_bf16_f32 v140, v116, v117
	v_lshlrev_b32_e32 v116, 16, v141
	v_and_b32_e32 v117, 0xffff0000, v141
	v_pk_mul_f32 v[114:115], v[114:115], v[116:117] op_sel_hi:[0,1]
	v_cvt_pk_bf16_f32 v141, v114, v115
	ds_read_b128 v[114:117], v157
	ds_read_b128 v[142:145], v157 offset:4352
	ds_read_b128 v[146:149], v157 offset:8704
	ds_read_b128 v[150:153], v157 offset:13056
	ds_read_b128 v[158:161], v157 offset:17408
	ds_read_b128 v[188:191], v157 offset:21760
	ds_read_b128 v[192:195], v157 offset:26112
	ds_read_b128 v[196:199], v157 offset:30464
	s_setprio 1
	s_waitcnt lgkmcnt(7)
	v_mfma_f32_16x16x32_bf16 v[32:35], v[114:117], v[96:99], v[32:35]
	v_mfma_f32_16x16x32_bf16 v[36:39], v[114:117], v[100:103], v[36:39]
	s_waitcnt lgkmcnt(6)
	v_mfma_f32_16x16x32_bf16 v[40:43], v[142:145], v[96:99], v[40:43]
	v_mfma_f32_16x16x32_bf16 v[44:47], v[142:145], v[100:103], v[44:47]
	s_waitcnt lgkmcnt(5)
	v_mfma_f32_16x16x32_bf16 v[48:51], v[146:149], v[96:99], v[48:51]
	v_mfma_f32_16x16x32_bf16 v[52:55], v[146:149], v[100:103], v[52:55]
	s_waitcnt lgkmcnt(4)
	v_mfma_f32_16x16x32_bf16 v[56:59], v[150:153], v[96:99], v[56:59]
	v_mfma_f32_16x16x32_bf16 v[60:63], v[150:153], v[100:103], v[60:63]
	s_waitcnt lgkmcnt(3)
	v_mfma_f32_16x16x32_bf16 v[64:67], v[158:161], v[96:99], v[64:67]
	v_mfma_f32_16x16x32_bf16 v[68:71], v[158:161], v[100:103], v[68:71]
	s_waitcnt lgkmcnt(2)
	v_mfma_f32_16x16x32_bf16 v[72:75], v[188:191], v[96:99], v[72:75]
	v_mfma_f32_16x16x32_bf16 v[76:79], v[188:191], v[100:103], v[76:79]
	s_waitcnt lgkmcnt(1)
	v_mfma_f32_16x16x32_bf16 v[80:83], v[192:195], v[96:99], v[80:83]
	v_mfma_f32_16x16x32_bf16 v[84:87], v[192:195], v[100:103], v[84:87]
	s_waitcnt lgkmcnt(0)
	v_mfma_f32_16x16x32_bf16 v[88:91], v[196:199], v[96:99], v[88:91]
	v_mfma_f32_16x16x32_bf16 v[92:95], v[196:199], v[100:103], v[92:95]
	s_setprio 0
	ds_read_b128 v[96:99], v157 offset:64
	ds_read_b128 v[100:103], v157 offset:4416
	ds_read_b128 v[114:117], v157 offset:8768
	ds_read_b128 v[142:145], v157 offset:13120
	ds_read_b128 v[146:149], v157 offset:17472
	ds_read_b128 v[150:153], v157 offset:21824
	ds_read_b128 v[158:161], v157 offset:26176
	ds_read_b128 v[188:191], v157 offset:30528
	s_setprio 1
	s_waitcnt lgkmcnt(7)
	v_mfma_f32_16x16x32_bf16 v[32:35], v[96:99], v[104:107], v[32:35]
	v_mfma_f32_16x16x32_bf16 v[36:39], v[96:99], v[118:121], v[36:39]
	s_waitcnt lgkmcnt(6)
	v_mfma_f32_16x16x32_bf16 v[40:43], v[100:103], v[104:107], v[40:43]
	v_mfma_f32_16x16x32_bf16 v[44:47], v[100:103], v[118:121], v[44:47]
	s_waitcnt lgkmcnt(5)
	v_mfma_f32_16x16x32_bf16 v[48:51], v[114:117], v[104:107], v[48:51]
	v_mfma_f32_16x16x32_bf16 v[52:55], v[114:117], v[118:121], v[52:55]
	s_waitcnt lgkmcnt(4)
	v_mfma_f32_16x16x32_bf16 v[56:59], v[142:145], v[104:107], v[56:59]
	v_mfma_f32_16x16x32_bf16 v[60:63], v[142:145], v[118:121], v[60:63]
	s_waitcnt lgkmcnt(3)
	v_mfma_f32_16x16x32_bf16 v[64:67], v[146:149], v[104:107], v[64:67]
	v_mfma_f32_16x16x32_bf16 v[68:71], v[146:149], v[118:121], v[68:71]
	s_waitcnt lgkmcnt(2)
	v_mfma_f32_16x16x32_bf16 v[72:75], v[150:153], v[104:107], v[72:75]
	v_mfma_f32_16x16x32_bf16 v[76:79], v[150:153], v[118:121], v[76:79]
	s_waitcnt lgkmcnt(1)
	v_mfma_f32_16x16x32_bf16 v[80:83], v[158:161], v[104:107], v[80:83]
	v_mfma_f32_16x16x32_bf16 v[84:87], v[158:161], v[118:121], v[84:87]
	s_waitcnt lgkmcnt(0)
	v_mfma_f32_16x16x32_bf16 v[88:91], v[188:191], v[104:107], v[88:91]
	v_mfma_f32_16x16x32_bf16 v[92:95], v[188:191], v[118:121], v[92:95]
	s_setprio 0
	ds_read_b128 v[96:99], v157 offset:128
	ds_read_b128 v[100:103], v157 offset:4480
	ds_read_b128 v[104:107], v157 offset:8832
	ds_read_b128 v[114:117], v157 offset:13184
	ds_read_b128 v[118:121], v157 offset:17536
	ds_read_b128 v[142:145], v157 offset:21888
	ds_read_b128 v[146:149], v157 offset:26240
	ds_read_b128 v[150:153], v157 offset:30592
	s_setprio 1
	s_waitcnt lgkmcnt(7)
	v_mfma_f32_16x16x32_bf16 v[32:35], v[96:99], v[122:125], v[32:35]
	v_mfma_f32_16x16x32_bf16 v[36:39], v[96:99], v[130:133], v[36:39]
	s_waitcnt lgkmcnt(6)
	v_mfma_f32_16x16x32_bf16 v[40:43], v[100:103], v[122:125], v[40:43]
	v_mfma_f32_16x16x32_bf16 v[44:47], v[100:103], v[130:133], v[44:47]
	s_waitcnt lgkmcnt(5)
	v_mfma_f32_16x16x32_bf16 v[48:51], v[104:107], v[122:125], v[48:51]
	v_mfma_f32_16x16x32_bf16 v[52:55], v[104:107], v[130:133], v[52:55]
	s_waitcnt lgkmcnt(4)
	v_mfma_f32_16x16x32_bf16 v[56:59], v[114:117], v[122:125], v[56:59]
	v_mfma_f32_16x16x32_bf16 v[60:63], v[114:117], v[130:133], v[60:63]
	s_waitcnt lgkmcnt(3)
	v_mfma_f32_16x16x32_bf16 v[64:67], v[118:121], v[122:125], v[64:67]
	v_mfma_f32_16x16x32_bf16 v[68:71], v[118:121], v[130:133], v[68:71]
	s_waitcnt lgkmcnt(2)
	v_mfma_f32_16x16x32_bf16 v[72:75], v[142:145], v[122:125], v[72:75]
	v_mfma_f32_16x16x32_bf16 v[76:79], v[142:145], v[130:133], v[76:79]
	s_waitcnt lgkmcnt(1)
	v_mfma_f32_16x16x32_bf16 v[80:83], v[146:149], v[122:125], v[80:83]
	v_mfma_f32_16x16x32_bf16 v[84:87], v[146:149], v[130:133], v[84:87]
	s_waitcnt lgkmcnt(0)
	v_mfma_f32_16x16x32_bf16 v[88:91], v[150:153], v[122:125], v[88:91]
	v_mfma_f32_16x16x32_bf16 v[92:95], v[150:153], v[130:133], v[92:95]
	s_setprio 0
	ds_read_b128 v[96:99], v157 offset:192
	ds_read_b128 v[100:103], v157 offset:4544
	ds_read_b128 v[104:107], v157 offset:8896
	ds_read_b128 v[114:117], v157 offset:13248
	ds_read_b128 v[118:121], v157 offset:17600
	ds_read_b128 v[122:125], v157 offset:21952
	ds_read_b128 v[130:133], v157 offset:26304
	ds_read_b128 v[142:145], v157 offset:30656
	s_setprio 1
	s_waitcnt lgkmcnt(7)
	v_mfma_f32_16x16x32_bf16 v[32:35], v[96:99], v[134:137], v[32:35]
	v_mfma_f32_16x16x32_bf16 v[36:39], v[96:99], v[138:141], v[36:39]
	s_waitcnt lgkmcnt(6)
	v_mfma_f32_16x16x32_bf16 v[40:43], v[100:103], v[134:137], v[40:43]
	v_mfma_f32_16x16x32_bf16 v[44:47], v[100:103], v[138:141], v[44:47]
	s_waitcnt lgkmcnt(5)
	v_mfma_f32_16x16x32_bf16 v[48:51], v[104:107], v[134:137], v[48:51]
	v_mfma_f32_16x16x32_bf16 v[52:55], v[104:107], v[138:141], v[52:55]
	s_waitcnt lgkmcnt(4)
	v_mfma_f32_16x16x32_bf16 v[56:59], v[114:117], v[134:137], v[56:59]
	v_mfma_f32_16x16x32_bf16 v[60:63], v[114:117], v[138:141], v[60:63]
	s_waitcnt lgkmcnt(3)
	v_mfma_f32_16x16x32_bf16 v[64:67], v[118:121], v[134:137], v[64:67]
	v_mfma_f32_16x16x32_bf16 v[68:71], v[118:121], v[138:141], v[68:71]
	s_waitcnt lgkmcnt(2)
	v_mfma_f32_16x16x32_bf16 v[72:75], v[122:125], v[134:137], v[72:75]
	v_mfma_f32_16x16x32_bf16 v[76:79], v[122:125], v[138:141], v[76:79]
	s_waitcnt lgkmcnt(1)
	v_mfma_f32_16x16x32_bf16 v[80:83], v[130:133], v[134:137], v[80:83]
	v_mfma_f32_16x16x32_bf16 v[84:87], v[130:133], v[138:141], v[84:87]
	s_waitcnt lgkmcnt(0)
	v_mfma_f32_16x16x32_bf16 v[88:91], v[142:145], v[134:137], v[88:91]
	v_mfma_f32_16x16x32_bf16 v[92:95], v[142:145], v[138:141], v[92:95]
	s_setprio 0
	s_nop 0
	v_lshlrev_b32_e32 v96, 16, v28
	v_and_b32_e32 v97, 0xffff0000, v28
	v_pk_mul_f32 v[96:97], v[112:113], v[96:97] op_sel_hi:[0,1]
	v_cvt_pk_bf16_f32 v28, v96, v97
	v_lshlrev_b32_e32 v96, 16, v29
	v_and_b32_e32 v97, 0xffff0000, v29
	v_pk_mul_f32 v[96:97], v[112:113], v[96:97] op_sel_hi:[0,1]
	v_cvt_pk_bf16_f32 v29, v96, v97
	v_lshlrev_b32_e32 v96, 16, v30
	v_and_b32_e32 v97, 0xffff0000, v30
	v_pk_mul_f32 v[96:97], v[112:113], v[96:97] op_sel_hi:[0,1]
	v_cvt_pk_bf16_f32 v30, v96, v97
	v_lshlrev_b32_e32 v96, 16, v31
	v_and_b32_e32 v97, 0xffff0000, v31
	v_pk_mul_f32 v[96:97], v[112:113], v[96:97] op_sel_hi:[0,1]
	v_cvt_pk_bf16_f32 v31, v96, v97
	v_lshlrev_b32_e32 v96, 16, v24
	v_and_b32_e32 v97, 0xffff0000, v24
	v_pk_mul_f32 v[96:97], v[110:111], v[96:97] op_sel_hi:[0,1]
	v_cvt_pk_bf16_f32 v24, v96, v97
	v_lshlrev_b32_e32 v96, 16, v25
	v_and_b32_e32 v97, 0xffff0000, v25
	v_pk_mul_f32 v[96:97], v[110:111], v[96:97] op_sel_hi:[0,1]
	v_cvt_pk_bf16_f32 v25, v96, v97
	v_lshlrev_b32_e32 v96, 16, v26
	v_and_b32_e32 v97, 0xffff0000, v26
	v_pk_mul_f32 v[96:97], v[110:111], v[96:97] op_sel_hi:[0,1]
	v_cvt_pk_bf16_f32 v26, v96, v97
	v_lshlrev_b32_e32 v96, 16, v27
	v_and_b32_e32 v97, 0xffff0000, v27
	v_pk_mul_f32 v[96:97], v[110:111], v[96:97] op_sel_hi:[0,1]
	v_cvt_pk_bf16_f32 v27, v96, v97
	v_lshlrev_b32_e32 v96, 16, v20
	v_and_b32_e32 v97, 0xffff0000, v20
	v_pk_mul_f32 v[96:97], v[112:113], v[96:97] op_sel_hi:[0,1]
	v_cvt_pk_bf16_f32 v20, v96, v97
	v_lshlrev_b32_e32 v96, 16, v21
	v_and_b32_e32 v97, 0xffff0000, v21
	v_pk_mul_f32 v[96:97], v[112:113], v[96:97] op_sel_hi:[0,1]
	v_cvt_pk_bf16_f32 v21, v96, v97
	v_lshlrev_b32_e32 v96, 16, v22
	v_and_b32_e32 v97, 0xffff0000, v22
	v_pk_mul_f32 v[96:97], v[112:113], v[96:97] op_sel_hi:[0,1]
	v_cvt_pk_bf16_f32 v22, v96, v97
	v_lshlrev_b32_e32 v96, 16, v23
	v_and_b32_e32 v97, 0xffff0000, v23
	v_pk_mul_f32 v[96:97], v[112:113], v[96:97] op_sel_hi:[0,1]
	v_cvt_pk_bf16_f32 v23, v96, v97
	v_lshlrev_b32_e32 v96, 16, v16
	v_and_b32_e32 v97, 0xffff0000, v16
	v_pk_mul_f32 v[96:97], v[110:111], v[96:97] op_sel_hi:[0,1]
	v_cvt_pk_bf16_f32 v16, v96, v97
	v_lshlrev_b32_e32 v96, 16, v17
	v_and_b32_e32 v97, 0xffff0000, v17
	v_pk_mul_f32 v[96:97], v[110:111], v[96:97] op_sel_hi:[0,1]
	v_cvt_pk_bf16_f32 v17, v96, v97
	v_lshlrev_b32_e32 v96, 16, v18
	v_and_b32_e32 v97, 0xffff0000, v18
	v_pk_mul_f32 v[96:97], v[110:111], v[96:97] op_sel_hi:[0,1]
	v_cvt_pk_bf16_f32 v18, v96, v97
	v_lshlrev_b32_e32 v96, 16, v19
	v_and_b32_e32 v97, 0xffff0000, v19
	v_pk_mul_f32 v[96:97], v[110:111], v[96:97] op_sel_hi:[0,1]
	v_cvt_pk_bf16_f32 v19, v96, v97
	v_lshlrev_b32_e32 v96, 16, v12
	v_and_b32_e32 v97, 0xffff0000, v12
	v_pk_mul_f32 v[96:97], v[112:113], v[96:97] op_sel_hi:[0,1]
	v_cvt_pk_bf16_f32 v12, v96, v97
	v_lshlrev_b32_e32 v96, 16, v13
	v_and_b32_e32 v97, 0xffff0000, v13
	v_pk_mul_f32 v[96:97], v[112:113], v[96:97] op_sel_hi:[0,1]
	v_cvt_pk_bf16_f32 v13, v96, v97
	v_lshlrev_b32_e32 v96, 16, v14
	v_and_b32_e32 v97, 0xffff0000, v14
	v_pk_mul_f32 v[96:97], v[112:113], v[96:97] op_sel_hi:[0,1]
	v_cvt_pk_bf16_f32 v14, v96, v97
	v_lshlrev_b32_e32 v96, 16, v15
	v_and_b32_e32 v97, 0xffff0000, v15
	v_pk_mul_f32 v[96:97], v[112:113], v[96:97] op_sel_hi:[0,1]
	v_cvt_pk_bf16_f32 v15, v96, v97
	v_lshlrev_b32_e32 v96, 16, v8
	v_and_b32_e32 v97, 0xffff0000, v8
	v_pk_mul_f32 v[96:97], v[110:111], v[96:97] op_sel_hi:[0,1]
	v_cvt_pk_bf16_f32 v8, v96, v97
	v_lshlrev_b32_e32 v96, 16, v9
	v_and_b32_e32 v97, 0xffff0000, v9
	v_pk_mul_f32 v[96:97], v[110:111], v[96:97] op_sel_hi:[0,1]
	v_cvt_pk_bf16_f32 v9, v96, v97
	v_lshlrev_b32_e32 v96, 16, v10
	v_and_b32_e32 v97, 0xffff0000, v10
	v_pk_mul_f32 v[96:97], v[110:111], v[96:97] op_sel_hi:[0,1]
	v_cvt_pk_bf16_f32 v10, v96, v97
	v_lshlrev_b32_e32 v96, 16, v11
	v_and_b32_e32 v97, 0xffff0000, v11
	v_pk_mul_f32 v[96:97], v[110:111], v[96:97] op_sel_hi:[0,1]
	v_cvt_pk_bf16_f32 v11, v96, v97
	v_lshlrev_b32_e32 v96, 16, v4
	v_and_b32_e32 v97, 0xffff0000, v4
	v_lshlrev_b32_e32 v4, 16, v5
	v_and_b32_e32 v5, 0xffff0000, v5
	v_pk_mul_f32 v[96:97], v[112:113], v[96:97] op_sel_hi:[0,1]
	v_pk_mul_f32 v[4:5], v[112:113], v[4:5] op_sel_hi:[0,1]
	v_cvt_pk_bf16_f32 v96, v96, v97
	v_cvt_pk_bf16_f32 v97, v4, v5
	v_lshlrev_b32_e32 v4, 16, v6
	v_and_b32_e32 v5, 0xffff0000, v6
	v_pk_mul_f32 v[4:5], v[112:113], v[4:5] op_sel_hi:[0,1]
	v_cvt_pk_bf16_f32 v98, v4, v5
	v_lshlrev_b32_e32 v4, 16, v7
	v_and_b32_e32 v5, 0xffff0000, v7
	v_pk_mul_f32 v[4:5], v[112:113], v[4:5] op_sel_hi:[0,1]
	v_cvt_pk_bf16_f32 v99, v4, v5
	s_nop 0
	v_lshlrev_b32_e32 v4, 16, v0
	v_and_b32_e32 v5, 0xffff0000, v0
	v_pk_mul_f32 v[4:5], v[110:111], v[4:5] op_sel_hi:[0,1]
	v_cvt_pk_bf16_f32 v0, v4, v5
	v_lshlrev_b32_e32 v4, 16, v1
	v_and_b32_e32 v5, 0xffff0000, v1
	v_pk_mul_f32 v[4:5], v[110:111], v[4:5] op_sel_hi:[0,1]
	v_cvt_pk_bf16_f32 v1, v4, v5
	v_lshlrev_b32_e32 v4, 16, v2
	v_and_b32_e32 v5, 0xffff0000, v2
	v_pk_mul_f32 v[4:5], v[110:111], v[4:5] op_sel_hi:[0,1]
	v_cvt_pk_bf16_f32 v2, v4, v5
	v_lshlrev_b32_e32 v4, 16, v3
	v_and_b32_e32 v5, 0xffff0000, v3
	v_pk_mul_f32 v[4:5], v[110:111], v[4:5] op_sel_hi:[0,1]
	v_cvt_pk_bf16_f32 v3, v4, v5
	ds_read_b128 v[4:7], v157 offset:34816
	ds_read_b128 v[100:103], v157 offset:39168
	ds_read_b128 v[104:107], v157 offset:43520
	ds_read_b128 v[110:113], v157 offset:47872
	ds_read_b128 v[114:117], v157 offset:52224
	ds_read_b128 v[118:121], v157 offset:56576
	ds_read_b128 v[122:125], v157 offset:60928
	ds_read_b128 v[130:133], v157 offset:65280
	s_setprio 1
	s_waitcnt lgkmcnt(7)
	v_mfma_f32_16x16x32_bf16 v[32:35], v[4:7], v[28:31], v[32:35]
	v_mfma_f32_16x16x32_bf16 v[4:7], v[4:7], v[24:27], v[36:39]
	s_waitcnt lgkmcnt(6)
	v_mfma_f32_16x16x32_bf16 v[36:39], v[100:103], v[28:31], v[40:43]
	v_mfma_f32_16x16x32_bf16 v[40:43], v[100:103], v[24:27], v[44:47]
	s_waitcnt lgkmcnt(5)
	v_mfma_f32_16x16x32_bf16 v[44:47], v[104:107], v[28:31], v[48:51]
	v_mfma_f32_16x16x32_bf16 v[48:51], v[104:107], v[24:27], v[52:55]
	s_waitcnt lgkmcnt(4)
	v_mfma_f32_16x16x32_bf16 v[52:55], v[110:113], v[28:31], v[56:59]
	v_mfma_f32_16x16x32_bf16 v[56:59], v[110:113], v[24:27], v[60:63]
	s_waitcnt lgkmcnt(3)
	v_mfma_f32_16x16x32_bf16 v[60:63], v[114:117], v[28:31], v[64:67]
	v_mfma_f32_16x16x32_bf16 v[64:67], v[114:117], v[24:27], v[68:71]
	s_waitcnt lgkmcnt(2)
	v_mfma_f32_16x16x32_bf16 v[68:71], v[118:121], v[28:31], v[72:75]
	v_mfma_f32_16x16x32_bf16 v[72:75], v[118:121], v[24:27], v[76:79]
	s_waitcnt lgkmcnt(1)
	v_mfma_f32_16x16x32_bf16 v[76:79], v[122:125], v[28:31], v[80:83]
	v_mfma_f32_16x16x32_bf16 v[80:83], v[122:125], v[24:27], v[84:87]
	s_waitcnt lgkmcnt(0)
	v_mfma_f32_16x16x32_bf16 v[28:31], v[130:133], v[28:31], v[88:91]
	v_mfma_f32_16x16x32_bf16 v[24:27], v[130:133], v[24:27], v[92:95]
	s_setprio 0
	ds_read_b128 v[84:87], v157 offset:34880
	ds_read_b128 v[88:91], v157 offset:39232
	ds_read_b128 v[92:95], v157 offset:43584
	ds_read_b128 v[100:103], v157 offset:47936
	ds_read_b128 v[104:107], v157 offset:52288
	ds_read_b128 v[110:113], v157 offset:56640
	ds_read_b128 v[114:117], v157 offset:60992
	ds_read_b128 v[118:121], v157 offset:65344
	s_setprio 1
	s_waitcnt lgkmcnt(7)
	v_mfma_f32_16x16x32_bf16 v[32:35], v[84:87], v[20:23], v[32:35]
	v_mfma_f32_16x16x32_bf16 v[4:7], v[84:87], v[16:19], v[4:7]
	s_waitcnt lgkmcnt(6)
	v_mfma_f32_16x16x32_bf16 v[36:39], v[88:91], v[20:23], v[36:39]
	v_mfma_f32_16x16x32_bf16 v[40:43], v[88:91], v[16:19], v[40:43]
	s_waitcnt lgkmcnt(5)
	v_mfma_f32_16x16x32_bf16 v[44:47], v[92:95], v[20:23], v[44:47]
	v_mfma_f32_16x16x32_bf16 v[48:51], v[92:95], v[16:19], v[48:51]
	s_waitcnt lgkmcnt(4)
	v_mfma_f32_16x16x32_bf16 v[52:55], v[100:103], v[20:23], v[52:55]
	v_mfma_f32_16x16x32_bf16 v[56:59], v[100:103], v[16:19], v[56:59]
	s_waitcnt lgkmcnt(3)
	v_mfma_f32_16x16x32_bf16 v[60:63], v[104:107], v[20:23], v[60:63]
	v_mfma_f32_16x16x32_bf16 v[64:67], v[104:107], v[16:19], v[64:67]
	s_waitcnt lgkmcnt(2)
	v_mfma_f32_16x16x32_bf16 v[68:71], v[110:113], v[20:23], v[68:71]
	v_mfma_f32_16x16x32_bf16 v[72:75], v[110:113], v[16:19], v[72:75]
	s_waitcnt lgkmcnt(1)
	v_mfma_f32_16x16x32_bf16 v[76:79], v[114:117], v[20:23], v[76:79]
	v_mfma_f32_16x16x32_bf16 v[80:83], v[114:117], v[16:19], v[80:83]
	s_waitcnt lgkmcnt(0)
	v_mfma_f32_16x16x32_bf16 v[20:23], v[118:121], v[20:23], v[28:31]
	v_mfma_f32_16x16x32_bf16 v[16:19], v[118:121], v[16:19], v[24:27]
	s_setprio 0
	s_nop 1
	ds_read_b128 v[24:27], v157 offset:34944
	ds_read_b128 v[28:31], v157 offset:39296
	ds_read_b128 v[84:87], v157 offset:43648
	ds_read_b128 v[88:91], v157 offset:48000
	ds_read_b128 v[92:95], v157 offset:52352
	ds_read_b128 v[100:103], v157 offset:56704
	ds_read_b128 v[104:107], v157 offset:61056
	ds_read_b128 v[110:113], v157 offset:65408
	s_setprio 1
	s_waitcnt lgkmcnt(7)
	v_mfma_f32_16x16x32_bf16 v[32:35], v[24:27], v[12:15], v[32:35]
	v_mfma_f32_16x16x32_bf16 v[4:7], v[24:27], v[8:11], v[4:7]
	s_waitcnt lgkmcnt(6)
	v_mfma_f32_16x16x32_bf16 v[24:27], v[28:31], v[12:15], v[36:39]
	v_mfma_f32_16x16x32_bf16 v[36:39], v[28:31], v[8:11], v[40:43]
	s_waitcnt lgkmcnt(5)
	v_mfma_f32_16x16x32_bf16 v[40:43], v[84:87], v[12:15], v[44:47]
	v_mfma_f32_16x16x32_bf16 v[44:47], v[84:87], v[8:11], v[48:51]
	s_waitcnt lgkmcnt(4)
	v_mfma_f32_16x16x32_bf16 v[48:51], v[88:91], v[12:15], v[52:55]
	v_mfma_f32_16x16x32_bf16 v[84:87], v[88:91], v[8:11], v[56:59]
	s_waitcnt lgkmcnt(3)
	v_mfma_f32_16x16x32_bf16 v[88:91], v[92:95], v[12:15], v[60:63]
	v_mfma_f32_16x16x32_bf16 v[64:67], v[92:95], v[8:11], v[64:67]
	s_waitcnt lgkmcnt(2)
	v_mfma_f32_16x16x32_bf16 v[68:71], v[100:103], v[12:15], v[68:71]
	v_mfma_f32_16x16x32_bf16 v[72:75], v[100:103], v[8:11], v[72:75]
	s_waitcnt lgkmcnt(1)
	v_mfma_f32_16x16x32_bf16 v[76:79], v[104:107], v[12:15], v[76:79]
	v_mfma_f32_16x16x32_bf16 v[80:83], v[104:107], v[8:11], v[80:83]
	s_waitcnt lgkmcnt(0)
	v_mfma_f32_16x16x32_bf16 v[92:95], v[110:113], v[12:15], v[20:23]
	v_mfma_f32_16x16x32_bf16 v[100:103], v[110:113], v[8:11], v[16:19]
	s_setprio 0
	ds_read_b128 v[8:11], v157 offset:35008
	ds_read_b128 v[12:15], v157 offset:39360
	ds_read_b128 v[16:19], v157 offset:43712
	ds_read_b128 v[104:107], v157 offset:48064
	ds_read_b128 v[110:113], v157 offset:52416
	ds_read_b128 v[114:117], v157 offset:56768
	ds_read_b128 v[118:121], v157 offset:61120
	ds_read_b128 v[122:125], v157 offset:65472
	s_setprio 1
	s_waitcnt lgkmcnt(7)
	v_mfma_f32_16x16x32_bf16 v[60:63], v[8:11], v[96:99], v[32:35]
	v_mfma_f32_16x16x32_bf16 v[28:31], v[8:11], v[0:3], v[4:7]
	s_waitcnt lgkmcnt(6)
	v_mfma_f32_16x16x32_bf16 v[56:59], v[12:15], v[96:99], v[24:27]
	v_mfma_f32_16x16x32_bf16 v[24:27], v[12:15], v[0:3], v[36:39]
	s_waitcnt lgkmcnt(5)
	v_mfma_f32_16x16x32_bf16 v[52:55], v[16:19], v[96:99], v[40:43]
	v_mfma_f32_16x16x32_bf16 v[20:23], v[16:19], v[0:3], v[44:47]
	s_waitcnt lgkmcnt(4)
	v_mfma_f32_16x16x32_bf16 v[48:51], v[104:107], v[96:99], v[48:51]
	v_mfma_f32_16x16x32_bf16 v[16:19], v[104:107], v[0:3], v[84:87]
	s_waitcnt lgkmcnt(3)
	v_mfma_f32_16x16x32_bf16 v[44:47], v[110:113], v[96:99], v[88:91]
	v_mfma_f32_16x16x32_bf16 v[12:15], v[110:113], v[0:3], v[64:67]
	s_waitcnt lgkmcnt(2)
	v_mfma_f32_16x16x32_bf16 v[40:43], v[114:117], v[96:99], v[68:71]
	v_mfma_f32_16x16x32_bf16 v[8:11], v[114:117], v[0:3], v[72:75]
	s_waitcnt lgkmcnt(1)
	v_mfma_f32_16x16x32_bf16 v[36:39], v[118:121], v[96:99], v[76:79]
	v_mfma_f32_16x16x32_bf16 v[4:7], v[118:121], v[0:3], v[80:83]
	s_waitcnt lgkmcnt(0)
	v_mfma_f32_16x16x32_bf16 v[32:35], v[122:125], v[96:99], v[92:95]
	v_mfma_f32_16x16x32_bf16 v[0:3], v[122:125], v[0:3], v[100:103]
	s_setprio 0
	v_mov_b32_e32 v64, v60
	v_mov_b32_e32 v65, v56
	v_mov_b32_e32 v66, v61
	v_mov_b32_e32 v67, v57
	v_pk_add_f32 v[64:65], v[64:65], v[66:67]
	v_mov_b32_e32 v66, v62
	v_mov_b32_e32 v67, v58
	v_pk_add_f32 v[64:65], v[66:67], v[64:65]
	v_mov_b32_e32 v66, v63
	v_mov_b32_e32 v67, v59
	v_pk_add_f32 v[64:65], v[66:67], v[64:65]
	v_mov_b32_e32 v66, v53
	v_add_f32_e32 v64, 0, v64
	v_add_f32_e32 v68, v64, v65
	v_mov_b32_e32 v64, v52
	v_mov_b32_e32 v65, v48
	v_mov_b32_e32 v67, v49
	v_pk_add_f32 v[64:65], v[64:65], v[66:67]
	v_mov_b32_e32 v66, v54
	v_mov_b32_e32 v67, v50
	v_pk_add_f32 v[64:65], v[66:67], v[64:65]
	v_mov_b32_e32 v66, v55
	v_mov_b32_e32 v67, v51
	v_pk_add_f32 v[64:65], v[66:67], v[64:65]
	v_mov_b32_e32 v66, v45
	v_add_f32_e32 v64, v68, v64
	v_add_f32_e32 v68, v64, v65
	v_mov_b32_e32 v64, v44
	v_mov_b32_e32 v65, v40
	v_mov_b32_e32 v67, v41
	v_pk_add_f32 v[64:65], v[64:65], v[66:67]
	v_mov_b32_e32 v66, v46
	v_mov_b32_e32 v67, v42
	v_pk_add_f32 v[64:65], v[66:67], v[64:65]
	v_mov_b32_e32 v66, v47
	v_mov_b32_e32 v67, v43
	v_pk_add_f32 v[64:65], v[66:67], v[64:65]
	v_mov_b32_e32 v66, v37
	v_add_f32_e32 v64, v68, v64
	v_add_f32_e32 v68, v64, v65
	v_mov_b32_e32 v64, v36
	v_mov_b32_e32 v65, v32
	v_mov_b32_e32 v67, v33
	v_pk_add_f32 v[64:65], v[64:65], v[66:67]
	v_mov_b32_e32 v66, v38
	v_mov_b32_e32 v67, v34
	v_pk_add_f32 v[64:65], v[66:67], v[64:65]
	v_mov_b32_e32 v66, v39
	v_mov_b32_e32 v67, v35
	v_pk_add_f32 v[64:65], v[66:67], v[64:65]
	s_load_dwordx16 s[40:55], s[0:1], 0x100
	v_add_f32_e32 v64, v68, v64
	v_add_f32_e32 v64, v64, v65
	ds_bpermute_b32 v65, v109, v64
	s_lshl_b32 s2, s57, 2
	v_readlane_b32 s4, v241, 38
	s_add_u32 s30, s4, s2
	v_readlane_b32 s2, v241, 39
	s_waitcnt lgkmcnt(0)
	v_add_f32_e32 v65, v64, v65
	ds_bpermute_b32 v66, v154, v65
	v_add_u32_e32 v64, s66, v108
	s_addc_u32 s31, s2, 0
	s_lshl_b32 s96, s57, 1
	v_lshlrev_b32_e32 v128, 1, v156
	s_waitcnt lgkmcnt(0)
	v_add_f32_e32 v69, v65, v66
	v_ashrrev_i32_e32 v65, 31, v64
	v_lshlrev_b64 v[66:67], 14, v[64:65]
	v_lshl_add_u64 v[66:67], s[52:53], 0, v[66:67]
	v_lshl_add_u64 v[66:67], v[66:67], 0, s[96:97]
	v_lshl_add_u64 v[78:79], v[66:67], 0, v[128:129]
	s_movk_i32 s38, 0x1000
	v_add_co_u32_e32 v66, vcc, s38, v78
	v_lshlrev_b32_e32 v68, 2, v156
	s_nop 0
	v_addc_co_u32_e32 v67, vcc, 0, v79, vcc
	global_load_dwordx2 v[80:81], v[66:67], off offset:2048
	global_load_dwordx4 v[70:73], v68, s[30:31]
	v_fmamk_f32 v77, v69, 0xbc000000, v61
	v_fmamk_f32 v76, v69, 0xbc000000, v60
	v_mul_f32_e32 v75, v77, v77
	v_fmac_f32_e32 v75, v76, v76
	v_fmamk_f32 v62, v69, 0xbc000000, v62
	v_fmac_f32_e32 v75, v62, v62
	v_fmac_f32_e32 v63, 0xbc000000, v69
	v_fmac_f32_e32 v75, v63, v63
	v_fmamk_f32 v60, v69, 0xbc000000, v56
	v_fmac_f32_e32 v75, v60, v60
	v_fmamk_f32 v61, v69, 0xbc000000, v57
	v_fmac_f32_e32 v75, v61, v61
	v_fmamk_f32 v58, v69, 0xbc000000, v58
	v_fmac_f32_e32 v75, v58, v58
	v_fmac_f32_e32 v59, 0xbc000000, v69
	v_fmac_f32_e32 v75, v59, v59
	v_fmamk_f32 v82, v69, 0xbc000000, v52
	v_fmac_f32_e32 v75, v82, v82
	v_fmamk_f32 v83, v69, 0xbc000000, v53
	v_fmac_f32_e32 v75, v83, v83
	v_fmamk_f32 v54, v69, 0xbc000000, v54
	v_fmac_f32_e32 v75, v54, v54
	v_fmac_f32_e32 v55, 0xbc000000, v69
	v_fmac_f32_e32 v75, v55, v55
	v_fmamk_f32 v66, v69, 0xbc000000, v48
	v_fmac_f32_e32 v75, v66, v66
	v_fmamk_f32 v67, v69, 0xbc000000, v49
	v_fmac_f32_e32 v75, v67, v67
	v_fmamk_f32 v50, v69, 0xbc000000, v50
	v_fmac_f32_e32 v75, v50, v50
	v_fmac_f32_e32 v51, 0xbc000000, v69
	v_fmac_f32_e32 v75, v51, v51
	v_fmamk_f32 v56, v69, 0xbc000000, v44
	v_fmac_f32_e32 v75, v56, v56
	v_fmamk_f32 v57, v69, 0xbc000000, v45
	v_fmac_f32_e32 v75, v57, v57
	v_fmamk_f32 v46, v69, 0xbc000000, v46
	v_fmac_f32_e32 v75, v46, v46
	v_fmac_f32_e32 v47, 0xbc000000, v69
	v_fmac_f32_e32 v75, v47, v47
	v_fmamk_f32 v52, v69, 0xbc000000, v40
	v_fmac_f32_e32 v75, v52, v52
	v_fmamk_f32 v53, v69, 0xbc000000, v41
	v_fmac_f32_e32 v75, v53, v53
	v_fmamk_f32 v42, v69, 0xbc000000, v42
	v_fmac_f32_e32 v75, v42, v42
	v_fmac_f32_e32 v43, 0xbc000000, v69
	v_mul_f32_e32 v74, 0x3c000000, v69
	v_fmac_f32_e32 v75, v43, v43
	v_pk_add_f32 v[40:41], v[36:37], v[74:75] op_sel_hi:[1,0] neg_lo:[0,1] neg_hi:[0,1]
	s_mov_b32 s2, 0x800000
	v_pk_mul_f32 v[40:41], v[40:41], v[40:41]
	s_load_dwordx16 s[4:19], s[0:1], 0x140
	v_add_f32_e32 v40, v40, v75
	v_add_f32_e32 v44, v41, v40
	v_pk_add_f32 v[40:41], v[38:39], v[74:75] op_sel_hi:[1,0] neg_lo:[0,1] neg_hi:[0,1]
	s_mov_b64 s[40:41], 0x1800
	v_pk_mul_f32 v[40:41], v[40:41], v[40:41]
	v_fmamk_f32 v37, v69, 0xbc000000, v37
	v_add_f32_e32 v40, v40, v44
	v_add_f32_e32 v44, v41, v40
	v_pk_add_f32 v[40:41], v[32:33], v[74:75] op_sel_hi:[1,0] neg_lo:[0,1] neg_hi:[0,1]
	v_fmamk_f32 v36, v69, 0xbc000000, v36
	v_pk_mul_f32 v[40:41], v[40:41], v[40:41]
	v_fmamk_f32 v39, v69, 0xbc000000, v39
	v_add_f32_e32 v40, v40, v44
	v_add_f32_e32 v44, v41, v40
	v_pk_add_f32 v[40:41], v[34:35], v[74:75] op_sel_hi:[1,0] neg_lo:[0,1] neg_hi:[0,1]
	v_fmac_f32_e32 v38, 0xbc000000, v69
	v_pk_mul_f32 v[40:41], v[40:41], v[40:41]
	v_fmamk_f32 v33, v69, 0xbc000000, v33
	v_add_f32_e32 v40, v40, v44
	v_add_f32_e32 v40, v41, v40
	ds_bpermute_b32 v41, v109, v40
	v_fmamk_f32 v32, v69, 0xbc000000, v32
	v_fmamk_f32 v35, v69, 0xbc000000, v35
	v_fmac_f32_e32 v34, 0xbc000000, v69
	s_add_i32 s70, s70, s64
	s_waitcnt lgkmcnt(0)
	v_add_f32_e32 v40, v40, v41
	ds_bpermute_b32 v41, v154, v40
	s_waitcnt vmcnt(1)
	v_and_b32_e32 v45, 0xffff0000, v80
	v_lshlrev_b32_e32 v48, 16, v81
	v_and_b32_e32 v49, 0xffff0000, v81
	s_cmpk_gt_i32 s70, 0x41f
	s_waitcnt lgkmcnt(0)
	v_add_f32_e32 v40, v40, v41
	v_fmamk_f32 v40, v40, 0x3c000000, v163
	v_mul_f32_e32 v41, 0x4b800000, v40
	v_cmp_gt_f32_e32 vcc, s2, v40
	s_nop 1
	v_cndmask_b32_e32 v40, v40, v41, vcc
	v_rsq_f32_e32 v40, v40
	s_nop 0
	v_mul_f32_e32 v41, 0x45800000, v40
	v_cndmask_b32_e32 v40, v40, v41, vcc
	v_lshlrev_b32_e32 v41, 16, v80
	v_mul_f32_e32 v41, 0xbfb8aa3b, v41
	v_exp_f32_e32 v41, v41
	v_lshlrev_b64 v[80:81], 11, v[64:65]
	v_add_f32_e32 v41, 1.0, v41
	v_rcp_f32_e32 v44, v41
	v_mul_f32_e32 v41, 0xbfb8aa3b, v45
	v_mul_f32_e32 v45, 0xbfb8aa3b, v48
	v_exp_f32_e32 v45, v45
	v_mul_f32_e32 v48, 0xbfb8aa3b, v49
	v_exp_f32_e32 v41, v41
	v_exp_f32_e32 v48, v48
	v_add_f32_e32 v45, 1.0, v45
	v_rcp_f32_e32 v74, v45
	v_add_f32_e32 v41, 1.0, v41
	v_add_f32_e32 v45, 1.0, v48
	v_rcp_f32_e32 v75, v45
	v_rcp_f32_e32 v45, v41
	v_lshl_add_u64 v[48:49], v[78:79], 0, s[40:41]
	global_load_dwordx2 v[204:205], v[48:49], off offset:32
	global_load_dwordx2 v[206:207], v[48:49], off offset:64
	global_load_dwordx2 v[208:209], v[48:49], off offset:96
	global_load_dwordx2 v[210:211], v[48:49], off offset:128
	global_load_dwordx2 v[216:217], v[48:49], off offset:160
	global_load_dwordx2 v[218:219], v[48:49], off offset:192
	global_load_dwordx2 v[220:221], v[48:49], off offset:224
	global_load_dwordx4 v[224:227], v68, s[30:31] offset:64
	global_load_dwordx4 v[228:231], v68, s[30:31] offset:128
	global_load_dwordx4 v[232:235], v68, s[30:31] offset:192
	global_load_dwordx4 v[236:239], v68, s[30:31] offset:256
	v_mov_b32_e32 v78, v6
	v_pk_mul_f32 v[62:63], v[62:63], v[74:75]
	v_pk_mul_f32 v[44:45], v[76:77], v[44:45]
	v_pk_mul_f32 v[62:63], v[62:63], v[40:41] op_sel_hi:[1,0]
	v_pk_mul_f32 v[44:45], v[44:45], v[40:41] op_sel_hi:[1,0]
	s_waitcnt vmcnt(0)
	v_pk_mul_f32 v[62:63], v[72:73], v[62:63]
	v_pk_mul_f32 v[44:45], v[70:71], v[44:45]
	v_cvt_pk_bf16_f32 v71, v62, v63
	v_cvt_pk_bf16_f32 v70, v44, v45
	v_lshl_add_u64 v[44:45], s[10:11], 0, v[80:81]
	v_lshl_add_u64 v[44:45], v[44:45], 0, s[96:97]
	v_lshl_add_u64 v[44:45], v[44:45], 0, v[128:129]
	global_store_dwordx2 v[44:45], v[70:71], off
	v_mov_b32_e32 v62, v204
	v_mov_b32_e32 v63, v205
	s_nop 0
	v_mov_b32_e32 v70, v224
	v_mov_b32_e32 v71, v225
	v_mov_b32_e32 v72, v226
	v_mov_b32_e32 v73, v227
	v_mov_b32_e32 v76, v5
	v_mov_b32_e32 v77, v1
	v_mov_b32_e32 v79, v2
	v_mov_b32_e32 v80, v7
	v_mov_b32_e32 v81, v3
	s_waitcnt vmcnt(1)
	v_lshlrev_b32_e32 v41, 16, v62
	v_mul_f32_e32 v41, 0xbfb8aa3b, v41
	v_exp_f32_e32 v41, v41
	v_and_b32_e32 v65, 0xffff0000, v62
	v_lshlrev_b32_e32 v74, 16, v63
	v_and_b32_e32 v63, 0xffff0000, v63
	v_add_f32_e32 v41, 1.0, v41
	v_rcp_f32_e32 v62, v41
	v_mul_f32_e32 v41, 0xbfb8aa3b, v65
	v_mul_f32_e32 v65, 0xbfb8aa3b, v74
	v_mul_f32_e32 v63, 0xbfb8aa3b, v63
	v_exp_f32_e32 v41, v41
	v_exp_f32_e32 v65, v65
	v_exp_f32_e32 v63, v63
	v_add_f32_e32 v41, 1.0, v41
	v_add_f32_e32 v65, 1.0, v65
	v_add_f32_e32 v63, 1.0, v63
	v_rcp_f32_e32 v74, v65
	v_rcp_f32_e32 v75, v63
	v_rcp_f32_e32 v63, v41
	v_pk_mul_f32 v[58:59], v[58:59], v[74:75]
	v_pk_mul_f32 v[60:61], v[60:61], v[62:63]
	v_pk_mul_f32 v[58:59], v[58:59], v[40:41] op_sel_hi:[1,0]
	v_pk_mul_f32 v[60:61], v[60:61], v[40:41] op_sel_hi:[1,0]
	s_waitcnt vmcnt(0)
	v_pk_mul_f32 v[58:59], v[72:73], v[58:59]
	v_pk_mul_f32 v[60:61], v[70:71], v[60:61]
	v_mov_b32_e32 v73, v11
	v_cvt_pk_bf16_f32 v60, v60, v61
	v_cvt_pk_bf16_f32 v61, v58, v59
	global_store_dwordx2 v[44:45], v[60:61], off offset:32
	v_mov_b32_e32 v62, v206
	v_mov_b32_e32 v63, v207
	s_nop 0
	v_mov_b32_e32 v58, v228
	v_mov_b32_e32 v59, v229
	v_mov_b32_e32 v60, v230
	v_mov_b32_e32 v61, v231
	v_mov_b32_e32 v74, v4
	v_mov_b32_e32 v75, v0
	s_waitcnt vmcnt(1)
	v_lshlrev_b32_e32 v41, 16, v62
	v_and_b32_e32 v62, 0xffff0000, v62
	v_lshlrev_b32_e32 v65, 16, v63
	v_and_b32_e32 v63, 0xffff0000, v63
	v_mul_f32_e32 v41, 0xbfb8aa3b, v41
	v_mul_f32_e32 v62, 0xbfb8aa3b, v62
	v_mul_f32_e32 v65, 0xbfb8aa3b, v65
	v_mul_f32_e32 v63, 0xbfb8aa3b, v63
	v_exp_f32_e32 v41, v41
	v_exp_f32_e32 v62, v62
	v_exp_f32_e32 v65, v65
	v_exp_f32_e32 v63, v63
	v_add_f32_e32 v41, 1.0, v41
	v_add_f32_e32 v72, 1.0, v62
	v_add_f32_e32 v65, 1.0, v65
	v_add_f32_e32 v63, 1.0, v63
	v_rcp_f32_e32 v62, v41
	v_rcp_f32_e32 v70, v65
	v_rcp_f32_e32 v71, v63
	v_rcp_f32_e32 v63, v72
	v_mov_b32_e32 v72, v15
	v_pk_mul_f32 v[54:55], v[54:55], v[70:71]
	v_pk_mul_f32 v[62:63], v[82:83], v[62:63]
	v_pk_mul_f32 v[54:55], v[54:55], v[40:41] op_sel_hi:[1,0]
	v_pk_mul_f32 v[62:63], v[62:63], v[40:41] op_sel_hi:[1,0]
	s_waitcnt vmcnt(0)
	v_pk_mul_f32 v[54:55], v[60:61], v[54:55]
	v_pk_mul_f32 v[58:59], v[58:59], v[62:63]
	v_mov_b32_e32 v70, v14
	v_cvt_pk_bf16_f32 v58, v58, v59
	v_cvt_pk_bf16_f32 v59, v54, v55
	global_store_dwordx2 v[44:45], v[58:59], off offset:64
	v_mov_b32_e32 v54, v208
	v_mov_b32_e32 v55, v209
	s_nop 0
	v_mov_b32_e32 v58, v232
	v_mov_b32_e32 v59, v233
	v_mov_b32_e32 v60, v234
	v_mov_b32_e32 v61, v235
	v_mov_b32_e32 v71, v10
	s_waitcnt vmcnt(1)
	v_lshlrev_b32_e32 v41, 16, v54
	v_and_b32_e32 v54, 0xffff0000, v54
	v_lshlrev_b32_e32 v62, 16, v55
	v_and_b32_e32 v55, 0xffff0000, v55
	v_mul_f32_e32 v41, 0xbfb8aa3b, v41
	v_mul_f32_e32 v54, 0xbfb8aa3b, v54
	v_mul_f32_e32 v62, 0xbfb8aa3b, v62
	v_mul_f32_e32 v55, 0xbfb8aa3b, v55
	v_exp_f32_e32 v41, v41
	v_exp_f32_e32 v54, v54
	v_exp_f32_e32 v62, v62
	v_exp_f32_e32 v55, v55
	v_add_f32_e32 v41, 1.0, v41
	v_add_f32_e32 v65, 1.0, v54
	v_add_f32_e32 v62, 1.0, v62
	v_add_f32_e32 v55, 1.0, v55
	v_rcp_f32_e32 v54, v41
	v_rcp_f32_e32 v62, v62
	v_rcp_f32_e32 v63, v55
	v_rcp_f32_e32 v55, v65
	v_pk_mul_f32 v[50:51], v[50:51], v[62:63]
	v_pk_mul_f32 v[54:55], v[66:67], v[54:55]
	v_pk_mul_f32 v[50:51], v[50:51], v[40:41] op_sel_hi:[1,0]
	v_pk_mul_f32 v[54:55], v[54:55], v[40:41] op_sel_hi:[1,0]
	s_waitcnt vmcnt(0)
	v_pk_mul_f32 v[50:51], v[60:61], v[50:51]
	v_pk_mul_f32 v[54:55], v[58:59], v[54:55]
	v_mov_b32_e32 v63, v8
	v_cvt_pk_bf16_f32 v54, v54, v55
	v_cvt_pk_bf16_f32 v55, v50, v51
	global_store_dwordx2 v[44:45], v[54:55], off offset:96
	v_mov_b32_e32 v50, v210
	v_mov_b32_e32 v51, v211
	v_mov_b32_e32 v58, v236
	v_mov_b32_e32 v59, v237
	v_mov_b32_e32 v60, v238
	v_mov_b32_e32 v61, v239
	v_mov_b32_e32 v66, v13
	v_mov_b32_e32 v67, v9
	s_waitcnt vmcnt(1)
	v_lshlrev_b32_e32 v41, 16, v50
	v_and_b32_e32 v50, 0xffff0000, v50
	v_lshlrev_b32_e32 v54, 16, v51
	v_and_b32_e32 v51, 0xffff0000, v51
	v_mul_f32_e32 v41, 0xbfb8aa3b, v41
	v_mul_f32_e32 v50, 0xbfb8aa3b, v50
	v_mul_f32_e32 v54, 0xbfb8aa3b, v54
	v_mul_f32_e32 v51, 0xbfb8aa3b, v51
	v_exp_f32_e32 v41, v41
	v_exp_f32_e32 v50, v50
	v_exp_f32_e32 v54, v54
	v_exp_f32_e32 v51, v51
	v_add_f32_e32 v41, 1.0, v41
	v_add_f32_e32 v62, 1.0, v50
	v_add_f32_e32 v54, 1.0, v54
	v_add_f32_e32 v51, 1.0, v51
	v_rcp_f32_e32 v50, v41
	v_rcp_f32_e32 v54, v54
	v_rcp_f32_e32 v55, v51
	v_rcp_f32_e32 v51, v62
	v_mov_b32_e32 v62, v12
	v_pk_mul_f32 v[46:47], v[46:47], v[54:55]
	v_pk_mul_f32 v[50:51], v[56:57], v[50:51]
	v_pk_mul_f32 v[46:47], v[46:47], v[40:41] op_sel_hi:[1,0]
	v_pk_mul_f32 v[50:51], v[50:51], v[40:41] op_sel_hi:[1,0]
	s_waitcnt vmcnt(0)
	v_pk_mul_f32 v[46:47], v[60:61], v[46:47]
	v_pk_mul_f32 v[50:51], v[58:59], v[50:51]
	v_mov_b32_e32 v59, v18
	v_cvt_pk_bf16_f32 v50, v50, v51
	v_cvt_pk_bf16_f32 v51, v46, v47
	global_store_dwordx2 v[44:45], v[50:51], off offset:128
	v_mov_b32_e32 v46, v216
	v_mov_b32_e32 v47, v217
	global_load_dwordx4 v[54:57], v68, s[30:31] offset:320
	v_mov_b32_e32 v60, v23
	v_mov_b32_e32 v61, v19
	s_waitcnt vmcnt(1)
	v_lshlrev_b32_e32 v41, 16, v46
	v_and_b32_e32 v46, 0xffff0000, v46
	v_lshlrev_b32_e32 v50, 16, v47
	v_and_b32_e32 v47, 0xffff0000, v47
	v_mul_f32_e32 v41, 0xbfb8aa3b, v41
	v_mul_f32_e32 v46, 0xbfb8aa3b, v46
	v_mul_f32_e32 v50, 0xbfb8aa3b, v50
	v_mul_f32_e32 v47, 0xbfb8aa3b, v47
	v_exp_f32_e32 v41, v41
	v_exp_f32_e32 v46, v46
	v_exp_f32_e32 v50, v50
	v_exp_f32_e32 v47, v47
	v_add_f32_e32 v41, 1.0, v41
	v_add_f32_e32 v58, 1.0, v46
	v_add_f32_e32 v50, 1.0, v50
	v_add_f32_e32 v47, 1.0, v47
	v_rcp_f32_e32 v46, v41
	v_rcp_f32_e32 v50, v50
	v_rcp_f32_e32 v51, v47
	v_rcp_f32_e32 v47, v58
	v_mov_b32_e32 v58, v22
	v_pk_mul_f32 v[42:43], v[42:43], v[50:51]
	v_pk_mul_f32 v[46:47], v[52:53], v[46:47]
	v_pk_mul_f32 v[42:43], v[40:41], v[42:43] op_sel_hi:[0,1]
	v_pk_mul_f32 v[46:47], v[40:41], v[46:47] op_sel_hi:[0,1]
	s_waitcnt vmcnt(0)
	v_pk_mul_f32 v[42:43], v[56:57], v[42:43]
	v_pk_mul_f32 v[46:47], v[54:55], v[46:47]
	v_mov_b32_e32 v55, v16
	v_cvt_pk_bf16_f32 v46, v46, v47
	v_cvt_pk_bf16_f32 v47, v42, v43
	global_store_dwordx2 v[44:45], v[46:47], off offset:160
	v_mov_b32_e32 v42, v218
	v_mov_b32_e32 v43, v219
	global_load_dwordx4 v[50:53], v68, s[30:31] offset:384
	v_mov_b32_e32 v56, v21
	v_mov_b32_e32 v57, v17
	s_waitcnt vmcnt(1)
	v_lshlrev_b32_e32 v41, 16, v42
	v_and_b32_e32 v42, 0xffff0000, v42
	v_lshlrev_b32_e32 v46, 16, v43
	v_and_b32_e32 v43, 0xffff0000, v43
	v_mul_f32_e32 v41, 0xbfb8aa3b, v41
	v_mul_f32_e32 v42, 0xbfb8aa3b, v42
	v_mul_f32_e32 v46, 0xbfb8aa3b, v46
	v_mul_f32_e32 v43, 0xbfb8aa3b, v43
	v_exp_f32_e32 v41, v41
	v_exp_f32_e32 v42, v42
	v_exp_f32_e32 v46, v46
	v_exp_f32_e32 v43, v43
	v_add_f32_e32 v41, 1.0, v41
	v_add_f32_e32 v54, 1.0, v42
	v_add_f32_e32 v46, 1.0, v46
	v_add_f32_e32 v43, 1.0, v43
	v_rcp_f32_e32 v42, v41
	v_rcp_f32_e32 v46, v46
	v_rcp_f32_e32 v47, v43
	v_rcp_f32_e32 v43, v54
	v_mov_b32_e32 v54, v20
	v_pk_mul_f32 v[38:39], v[38:39], v[46:47]
	v_pk_mul_f32 v[36:37], v[36:37], v[42:43]
	v_pk_mul_f32 v[38:39], v[40:41], v[38:39] op_sel_hi:[0,1]
	v_pk_mul_f32 v[36:37], v[40:41], v[36:37] op_sel_hi:[0,1]
	s_waitcnt vmcnt(0)
	v_pk_mul_f32 v[38:39], v[52:53], v[38:39]
	v_pk_mul_f32 v[36:37], v[50:51], v[36:37]
	v_mov_b32_e32 v42, v29
	v_cvt_pk_bf16_f32 v36, v36, v37
	v_cvt_pk_bf16_f32 v37, v38, v39
	global_store_dwordx2 v[44:45], v[36:37], off offset:192
	v_mov_b32_e32 v36, v220
	v_mov_b32_e32 v37, v221
	v_mov_b32_e32 v38, v28
	global_load_dwordx4 v[46:49], v68, s[30:31] offset:448
	v_mov_b32_e32 v39, v24
	v_mov_b32_e32 v43, v25
	v_mov_b32_e32 v50, v30
	v_mov_b32_e32 v51, v26
	v_pk_add_f32 v[38:39], v[38:39], v[42:43]
	v_mov_b32_e32 v52, v31
	v_mov_b32_e32 v53, v27
	v_pk_add_f32 v[38:39], v[50:51], v[38:39]
	v_pk_add_f32 v[42:43], v[54:55], v[56:57]
	v_pk_add_f32 v[38:39], v[52:53], v[38:39]
	v_pk_add_f32 v[42:43], v[58:59], v[42:43]
	v_add_f32_e32 v38, 0, v38
	v_pk_add_f32 v[54:55], v[62:63], v[66:67]
	v_pk_add_f32 v[42:43], v[60:61], v[42:43]
	v_add_f32_e32 v38, v38, v39
	v_pk_add_f32 v[50:51], v[70:71], v[54:55]
	v_add_f32_e32 v38, v38, v42
	v_pk_add_f32 v[56:57], v[74:75], v[76:77]
	v_pk_add_f32 v[50:51], v[72:73], v[50:51]
	v_add_f32_e32 v38, v38, v43
	v_pk_add_f32 v[54:55], v[78:79], v[56:57]
	v_add_f32_e32 v38, v38, v50
	v_pk_add_f32 v[52:53], v[80:81], v[54:55]
	v_add_f32_e32 v38, v38, v51
	v_add_f32_e32 v38, v38, v52
	v_add_f32_e32 v41, v38, v53
	v_add_u32_e32 v62, 16, v64
	ds_bpermute_b32 v50, v109, v41
	v_ashrrev_i32_e32 v63, 31, v62
	v_lshlrev_b64 v[38:39], 14, v[62:63]
	v_lshl_add_u64 v[38:39], s[52:53], 0, v[38:39]
	v_lshl_add_u64 v[38:39], v[38:39], 0, s[96:97]
	v_lshl_add_u64 v[42:43], v[38:39], 0, v[128:129]
	s_waitcnt lgkmcnt(0)
	v_add_f32_e32 v38, v41, v50
	ds_bpermute_b32 v39, v154, v38
	v_add_co_u32_e32 v50, vcc, s38, v42
	s_waitcnt lgkmcnt(0)
	v_add_f32_e32 v38, v38, v39
	v_fmamk_f32 v54, v38, 0xbc000000, v28
	v_fmamk_f32 v55, v38, 0xbc000000, v29
	v_addc_co_u32_e32 v51, vcc, 0, v43, vcc
	v_mul_f32_e32 v39, v55, v55
	v_fmamk_f32 v30, v38, 0xbc000000, v30
	v_fmac_f32_e32 v39, v54, v54
	v_fmac_f32_e32 v31, 0xbc000000, v38
	v_fmac_f32_e32 v39, v30, v30
	v_fmac_f32_e32 v39, v31, v31
	v_fmamk_f32 v26, v38, 0xbc000000, v26
	v_fmac_f32_e32 v27, 0xbc000000, v38
	v_fmamk_f32 v22, v38, 0xbc000000, v22
	v_fmac_f32_e32 v23, 0xbc000000, v38
	v_fmamk_f32 v18, v38, 0xbc000000, v18
	v_fmac_f32_e32 v19, 0xbc000000, v38
	v_fmamk_f32 v14, v38, 0xbc000000, v14
	v_fmac_f32_e32 v15, 0xbc000000, v38
	v_mul_f32_e32 v52, 0x3c000000, v38
	v_fmamk_f32 v10, v38, 0xbc000000, v10
	v_fmac_f32_e32 v11, 0xbc000000, v38
	s_waitcnt vmcnt(1)
	v_lshlrev_b32_e32 v28, 16, v36
	v_and_b32_e32 v29, 0xffff0000, v36
	v_lshlrev_b32_e32 v36, 16, v37
	v_and_b32_e32 v37, 0xffff0000, v37
	v_mul_f32_e32 v28, 0xbfb8aa3b, v28
	v_mul_f32_e32 v29, 0xbfb8aa3b, v29
	v_mul_f32_e32 v36, 0xbfb8aa3b, v36
	v_mul_f32_e32 v37, 0xbfb8aa3b, v37
	v_exp_f32_e32 v28, v28
	v_exp_f32_e32 v29, v29
	v_exp_f32_e32 v36, v36
	v_exp_f32_e32 v37, v37
	v_add_f32_e32 v28, 1.0, v28
	v_add_f32_e32 v29, 1.0, v29
	v_add_f32_e32 v36, 1.0, v36
	v_add_f32_e32 v37, 1.0, v37
	v_rcp_f32_e32 v28, v28
	v_rcp_f32_e32 v36, v36
	v_rcp_f32_e32 v37, v37
	v_rcp_f32_e32 v29, v29
	v_pk_mul_f32 v[34:35], v[34:35], v[36:37]
	v_pk_mul_f32 v[28:29], v[32:33], v[28:29]
	v_pk_mul_f32 v[32:33], v[40:41], v[34:35] op_sel_hi:[0,1]
	v_pk_mul_f32 v[28:29], v[40:41], v[28:29] op_sel_hi:[0,1]
	s_waitcnt vmcnt(0)
	v_pk_mul_f32 v[32:33], v[48:49], v[32:33]
	v_pk_mul_f32 v[28:29], v[46:47], v[28:29]
	v_pk_add_f32 v[46:47], v[2:3], v[52:53] op_sel_hi:[1,0] neg_lo:[0,1] neg_hi:[0,1]
	v_cvt_pk_bf16_f32 v28, v28, v29
	v_cvt_pk_bf16_f32 v29, v32, v33
	global_store_dwordx2 v[44:45], v[28:29], off offset:224
	global_load_dwordx2 v[40:41], v[50:51], off offset:2048
	global_load_dwordx4 v[34:37], v68, s[30:31]
	v_fmamk_f32 v44, v38, 0xbc000000, v24
	v_fmamk_f32 v45, v38, 0xbc000000, v25
	v_fmac_f32_e32 v39, v44, v44
	v_fmac_f32_e32 v39, v45, v45
	v_fmac_f32_e32 v39, v26, v26
	v_fmamk_f32 v32, v38, 0xbc000000, v20
	v_fmac_f32_e32 v39, v27, v27
	v_fmamk_f32 v33, v38, 0xbc000000, v21
	v_fmac_f32_e32 v39, v32, v32
	v_fmac_f32_e32 v39, v33, v33
	v_fmac_f32_e32 v39, v22, v22
	v_fmamk_f32 v28, v38, 0xbc000000, v16
	v_fmac_f32_e32 v39, v23, v23
	v_fmamk_f32 v29, v38, 0xbc000000, v17
	v_fmac_f32_e32 v39, v28, v28
	v_fmac_f32_e32 v39, v29, v29
	v_fmac_f32_e32 v39, v18, v18
	v_fmamk_f32 v24, v38, 0xbc000000, v12
	v_fmac_f32_e32 v39, v19, v19
	v_fmamk_f32 v25, v38, 0xbc000000, v13
	v_fmac_f32_e32 v39, v24, v24
	v_fmac_f32_e32 v39, v25, v25
	v_fmac_f32_e32 v39, v14, v14
	v_fmamk_f32 v16, v38, 0xbc000000, v8
	v_fmac_f32_e32 v39, v15, v15
	v_fmamk_f32 v17, v38, 0xbc000000, v9
	v_fmac_f32_e32 v39, v16, v16
	v_fmac_f32_e32 v39, v17, v17
	v_pk_add_f32 v[8:9], v[4:5], v[52:53] op_sel_hi:[1,0] neg_lo:[0,1] neg_hi:[0,1]
	v_fmac_f32_e32 v39, v10, v10
	v_pk_mul_f32 v[8:9], v[8:9], v[8:9]
	v_fmac_f32_e32 v39, v11, v11
	v_pk_add_f32 v[12:13], v[6:7], v[52:53] op_sel_hi:[1,0] neg_lo:[0,1] neg_hi:[0,1]
	v_add_f32_e32 v8, v8, v39
	v_pk_mul_f32 v[12:13], v[12:13], v[12:13]
	v_add_f32_e32 v8, v9, v8
	v_pk_add_f32 v[20:21], v[0:1], v[52:53] op_sel_hi:[1,0] neg_lo:[0,1] neg_hi:[0,1]
	v_add_f32_e32 v8, v12, v8
	v_pk_mul_f32 v[20:21], v[20:21], v[20:21]
	v_add_f32_e32 v8, v13, v8
	v_add_f32_e32 v8, v20, v8
	v_pk_mul_f32 v[46:47], v[46:47], v[46:47]
	v_add_f32_e32 v8, v21, v8
	v_add_f32_e32 v8, v46, v8
	v_add_f32_e32 v12, v47, v8
	ds_bpermute_b32 v13, v109, v12
	v_lshl_add_u64 v[20:21], v[42:43], 0, s[40:41]
	global_load_dwordx2 v[222:223], v[20:21], off offset:32
	global_load_dwordx2 v[224:225], v[20:21], off offset:64
	global_load_dwordx2 v[226:227], v[20:21], off offset:96
	global_load_dwordx2 v[228:229], v[20:21], off offset:128
	global_load_dwordx2 v[230:231], v[20:21], off offset:160
	global_load_dwordx2 v[232:233], v[20:21], off offset:192
	global_load_dwordx2 v[234:235], v[20:21], off offset:224
	global_load_dwordx4 v[204:207], v68, s[30:31] offset:64
	global_load_dwordx4 v[208:211], v68, s[30:31] offset:128
	global_load_dwordx4 v[216:219], v68, s[30:31] offset:192
	global_load_dwordx4 v[236:239], v68, s[30:31] offset:256
	v_lshlrev_b64 v[8:9], 11, v[62:63]
	v_lshl_add_u64 v[8:9], s[10:11], 0, v[8:9]
	v_lshl_add_u64 v[8:9], v[8:9], 0, s[96:97]
	s_waitcnt lgkmcnt(0)
	v_add_f32_e32 v12, v12, v13
	ds_bpermute_b32 v13, v154, v12
	v_lshl_add_u64 v[8:9], v[8:9], 0, v[128:129]
	v_fmamk_f32 v5, v38, 0xbc000000, v5
	v_fmamk_f32 v4, v38, 0xbc000000, v4
	v_fmamk_f32 v7, v38, 0xbc000000, v7
	s_waitcnt lgkmcnt(0)
	v_add_f32_e32 v12, v12, v13
	v_fmamk_f32 v12, v12, 0x3c000000, v163
	v_mul_f32_e32 v13, 0x4b800000, v12
	v_cmp_gt_f32_e32 vcc, s2, v12
	v_fmac_f32_e32 v6, 0xbc000000, v38
	v_fmamk_f32 v1, v38, 0xbc000000, v1
	v_cndmask_b32_e32 v12, v12, v13, vcc
	v_rsq_f32_e32 v12, v12
	v_fmamk_f32 v0, v38, 0xbc000000, v0
	v_fmamk_f32 v3, v38, 0xbc000000, v3
	v_fmac_f32_e32 v2, 0xbc000000, v38
	s_waitcnt vmcnt(1)
	v_lshlrev_b32_e32 v13, 16, v40
	v_and_b32_e32 v39, 0xffff0000, v40
	v_lshlrev_b32_e32 v40, 16, v41
	v_and_b32_e32 v41, 0xffff0000, v41
	v_mul_f32_e32 v13, 0xbfb8aa3b, v13
	v_mul_f32_e32 v39, 0xbfb8aa3b, v39
	v_mul_f32_e32 v40, 0xbfb8aa3b, v40
	v_mul_f32_e32 v41, 0xbfb8aa3b, v41
	v_exp_f32_e32 v13, v13
	v_exp_f32_e32 v39, v39
	v_exp_f32_e32 v40, v40
	v_exp_f32_e32 v41, v41
	v_add_f32_e32 v13, 1.0, v13
	v_add_f32_e32 v39, 1.0, v39
	v_add_f32_e32 v42, 1.0, v40
	v_add_f32_e32 v41, 1.0, v41
	v_rcp_f32_e32 v40, v13
	v_rcp_f32_e32 v42, v42
	v_rcp_f32_e32 v43, v41
	v_rcp_f32_e32 v41, v39
	v_mul_f32_e32 v13, 0x45800000, v12
	v_cndmask_b32_e32 v12, v12, v13, vcc
	v_pk_mul_f32 v[30:31], v[30:31], v[42:43]
	v_pk_mul_f32 v[40:41], v[54:55], v[40:41]
	v_pk_mul_f32 v[30:31], v[30:31], v[12:13] op_sel_hi:[1,0]
	v_pk_mul_f32 v[40:41], v[40:41], v[12:13] op_sel_hi:[1,0]
	s_waitcnt vmcnt(0)
	v_pk_mul_f32 v[30:31], v[36:37], v[30:31]
	v_pk_mul_f32 v[34:35], v[34:35], v[40:41]
	s_nop 0
	v_cvt_pk_bf16_f32 v34, v34, v35
	v_cvt_pk_bf16_f32 v35, v30, v31
	global_store_dwordx2 v[8:9], v[34:35], off
	v_mov_b32_e32 v30, v222
	v_mov_b32_e32 v31, v223
	s_nop 0
	v_mov_b32_e32 v34, v204
	v_mov_b32_e32 v35, v205
	v_mov_b32_e32 v36, v206
	v_mov_b32_e32 v37, v207
	s_waitcnt vmcnt(1)
	v_lshlrev_b32_e32 v13, 16, v30
	v_and_b32_e32 v30, 0xffff0000, v30
	v_lshlrev_b32_e32 v39, 16, v31
	v_and_b32_e32 v31, 0xffff0000, v31
	v_mul_f32_e32 v13, 0xbfb8aa3b, v13
	v_mul_f32_e32 v30, 0xbfb8aa3b, v30
	v_mul_f32_e32 v39, 0xbfb8aa3b, v39
	v_mul_f32_e32 v31, 0xbfb8aa3b, v31
	v_exp_f32_e32 v13, v13
	v_exp_f32_e32 v30, v30
	v_exp_f32_e32 v39, v39
	v_exp_f32_e32 v31, v31
	v_add_f32_e32 v13, 1.0, v13
	v_add_f32_e32 v42, 1.0, v30
	v_add_f32_e32 v39, 1.0, v39
	v_add_f32_e32 v31, 1.0, v31
	v_rcp_f32_e32 v30, v13
	v_rcp_f32_e32 v40, v39
	v_rcp_f32_e32 v41, v31
	v_rcp_f32_e32 v31, v42
	v_pk_mul_f32 v[26:27], v[26:27], v[40:41]
	v_pk_mul_f32 v[30:31], v[44:45], v[30:31]
	v_pk_mul_f32 v[26:27], v[26:27], v[12:13] op_sel_hi:[1,0]
	v_pk_mul_f32 v[30:31], v[30:31], v[12:13] op_sel_hi:[1,0]
	s_waitcnt vmcnt(0)
	v_pk_mul_f32 v[26:27], v[36:37], v[26:27]
	v_pk_mul_f32 v[30:31], v[34:35], v[30:31]
	s_nop 0
	v_cvt_pk_bf16_f32 v30, v30, v31
	v_cvt_pk_bf16_f32 v31, v26, v27
	global_store_dwordx2 v[8:9], v[30:31], off offset:32
	v_mov_b32_e32 v26, v224
	v_mov_b32_e32 v27, v225
	v_mov_b32_e32 v34, v208
	v_mov_b32_e32 v35, v209
	v_mov_b32_e32 v36, v210
	v_mov_b32_e32 v37, v211
	s_waitcnt vmcnt(1)
	v_lshlrev_b32_e32 v13, 16, v26
	v_and_b32_e32 v26, 0xffff0000, v26
	v_lshlrev_b32_e32 v30, 16, v27
	v_and_b32_e32 v27, 0xffff0000, v27
	v_mul_f32_e32 v13, 0xbfb8aa3b, v13
	v_mul_f32_e32 v26, 0xbfb8aa3b, v26
	v_mul_f32_e32 v30, 0xbfb8aa3b, v30
	v_mul_f32_e32 v27, 0xbfb8aa3b, v27
	v_exp_f32_e32 v13, v13
	v_exp_f32_e32 v26, v26
	v_exp_f32_e32 v30, v30
	v_exp_f32_e32 v27, v27
	v_add_f32_e32 v13, 1.0, v13
	v_add_f32_e32 v39, 1.0, v26
	v_add_f32_e32 v30, 1.0, v30
	v_add_f32_e32 v27, 1.0, v27
	v_rcp_f32_e32 v26, v13
	v_rcp_f32_e32 v30, v30
	v_rcp_f32_e32 v31, v27
	v_rcp_f32_e32 v27, v39
	v_pk_mul_f32 v[22:23], v[22:23], v[30:31]
	v_pk_mul_f32 v[26:27], v[32:33], v[26:27]
	v_pk_mul_f32 v[22:23], v[22:23], v[12:13] op_sel_hi:[1,0]
	v_pk_mul_f32 v[26:27], v[26:27], v[12:13] op_sel_hi:[1,0]
	s_waitcnt vmcnt(0)
	v_pk_mul_f32 v[22:23], v[36:37], v[22:23]
	v_pk_mul_f32 v[26:27], v[34:35], v[26:27]
	s_nop 0
	v_cvt_pk_bf16_f32 v26, v26, v27
	v_cvt_pk_bf16_f32 v27, v22, v23
	global_store_dwordx2 v[8:9], v[26:27], off offset:64
	v_mov_b32_e32 v22, v226
	v_mov_b32_e32 v23, v227
	v_mov_b32_e32 v30, v216
	v_mov_b32_e32 v31, v217
	v_mov_b32_e32 v32, v218
	v_mov_b32_e32 v33, v219
	s_waitcnt vmcnt(1)
	v_lshlrev_b32_e32 v13, 16, v22
	v_and_b32_e32 v22, 0xffff0000, v22
	v_lshlrev_b32_e32 v26, 16, v23
	v_and_b32_e32 v23, 0xffff0000, v23
	v_mul_f32_e32 v13, 0xbfb8aa3b, v13
	v_mul_f32_e32 v22, 0xbfb8aa3b, v22
	v_mul_f32_e32 v26, 0xbfb8aa3b, v26
	v_mul_f32_e32 v23, 0xbfb8aa3b, v23
	v_exp_f32_e32 v13, v13
	v_exp_f32_e32 v22, v22
	v_exp_f32_e32 v26, v26
	v_exp_f32_e32 v23, v23
	v_add_f32_e32 v13, 1.0, v13
	v_add_f32_e32 v34, 1.0, v22
	v_add_f32_e32 v26, 1.0, v26
	v_add_f32_e32 v23, 1.0, v23
	v_rcp_f32_e32 v22, v13
	v_rcp_f32_e32 v26, v26
	v_rcp_f32_e32 v27, v23
	v_rcp_f32_e32 v23, v34
	v_pk_mul_f32 v[18:19], v[18:19], v[26:27]
	v_pk_mul_f32 v[22:23], v[28:29], v[22:23]
	v_pk_mul_f32 v[18:19], v[18:19], v[12:13] op_sel_hi:[1,0]
	v_pk_mul_f32 v[22:23], v[22:23], v[12:13] op_sel_hi:[1,0]
	s_waitcnt vmcnt(0)
	v_pk_mul_f32 v[18:19], v[32:33], v[18:19]
	v_pk_mul_f32 v[22:23], v[30:31], v[22:23]
	s_nop 0
	v_cvt_pk_bf16_f32 v22, v22, v23
	v_cvt_pk_bf16_f32 v23, v18, v19
	global_store_dwordx2 v[8:9], v[22:23], off offset:96
	v_mov_b32_e32 v18, v228
	v_mov_b32_e32 v19, v229
	v_mov_b32_e32 v26, v236
	v_mov_b32_e32 v27, v237
	v_mov_b32_e32 v28, v238
	v_mov_b32_e32 v29, v239
	s_waitcnt vmcnt(1)
	v_lshlrev_b32_e32 v13, 16, v18
	v_and_b32_e32 v18, 0xffff0000, v18
	v_lshlrev_b32_e32 v22, 16, v19
	v_and_b32_e32 v19, 0xffff0000, v19
	v_mul_f32_e32 v13, 0xbfb8aa3b, v13
	v_mul_f32_e32 v18, 0xbfb8aa3b, v18
	v_mul_f32_e32 v22, 0xbfb8aa3b, v22
	v_mul_f32_e32 v19, 0xbfb8aa3b, v19
	v_exp_f32_e32 v13, v13
	v_exp_f32_e32 v18, v18
	v_exp_f32_e32 v22, v22
	v_exp_f32_e32 v19, v19
	v_add_f32_e32 v13, 1.0, v13
	v_add_f32_e32 v30, 1.0, v18
	v_add_f32_e32 v22, 1.0, v22
	v_add_f32_e32 v19, 1.0, v19
	v_rcp_f32_e32 v18, v13
	v_rcp_f32_e32 v22, v22
	v_rcp_f32_e32 v23, v19
	v_rcp_f32_e32 v19, v30
	v_pk_mul_f32 v[14:15], v[14:15], v[22:23]
	v_pk_mul_f32 v[18:19], v[24:25], v[18:19]
	v_pk_mul_f32 v[14:15], v[14:15], v[12:13] op_sel_hi:[1,0]
	v_pk_mul_f32 v[18:19], v[18:19], v[12:13] op_sel_hi:[1,0]
	s_waitcnt vmcnt(0)
	v_pk_mul_f32 v[14:15], v[28:29], v[14:15]
	v_pk_mul_f32 v[18:19], v[26:27], v[18:19]
	s_nop 0
	v_cvt_pk_bf16_f32 v18, v18, v19
	v_cvt_pk_bf16_f32 v19, v14, v15
	global_store_dwordx2 v[8:9], v[18:19], off offset:128
	v_mov_b32_e32 v14, v230
	v_mov_b32_e32 v15, v231
	global_load_dwordx4 v[22:25], v68, s[30:31] offset:320
	s_waitcnt vmcnt(1)
	v_lshlrev_b32_e32 v13, 16, v14
	v_and_b32_e32 v14, 0xffff0000, v14
	v_lshlrev_b32_e32 v18, 16, v15
	v_and_b32_e32 v15, 0xffff0000, v15
	v_mul_f32_e32 v13, 0xbfb8aa3b, v13
	v_mul_f32_e32 v14, 0xbfb8aa3b, v14
	v_mul_f32_e32 v18, 0xbfb8aa3b, v18
	v_mul_f32_e32 v15, 0xbfb8aa3b, v15
	v_exp_f32_e32 v13, v13
	v_exp_f32_e32 v14, v14
	v_exp_f32_e32 v18, v18
	v_exp_f32_e32 v15, v15
	v_add_f32_e32 v13, 1.0, v13
	v_add_f32_e32 v26, 1.0, v14
	v_add_f32_e32 v18, 1.0, v18
	v_add_f32_e32 v15, 1.0, v15
	v_rcp_f32_e32 v14, v13
	v_rcp_f32_e32 v18, v18
	v_rcp_f32_e32 v19, v15
	v_rcp_f32_e32 v15, v26
	v_pk_mul_f32 v[10:11], v[10:11], v[18:19]
	v_pk_mul_f32 v[14:15], v[16:17], v[14:15]
	v_pk_mul_f32 v[10:11], v[12:13], v[10:11] op_sel_hi:[0,1]
	v_pk_mul_f32 v[14:15], v[12:13], v[14:15] op_sel_hi:[0,1]
	s_waitcnt vmcnt(0)
	v_pk_mul_f32 v[10:11], v[24:25], v[10:11]
	v_pk_mul_f32 v[14:15], v[22:23], v[14:15]
	s_nop 0
	v_cvt_pk_bf16_f32 v14, v14, v15
	v_cvt_pk_bf16_f32 v15, v10, v11
	global_store_dwordx2 v[8:9], v[14:15], off offset:160
	v_mov_b32_e32 v10, v232
	v_mov_b32_e32 v11, v233
	s_nop 0
	global_load_dwordx4 v[14:17], v68, s[30:31] offset:384
	s_waitcnt vmcnt(1)
	v_lshlrev_b32_e32 v13, 16, v10
	v_and_b32_e32 v10, 0xffff0000, v10
	v_lshlrev_b32_e32 v18, 16, v11
	v_and_b32_e32 v11, 0xffff0000, v11
	v_mul_f32_e32 v13, 0xbfb8aa3b, v13
	v_mul_f32_e32 v10, 0xbfb8aa3b, v10
	v_mul_f32_e32 v18, 0xbfb8aa3b, v18
	v_mul_f32_e32 v11, 0xbfb8aa3b, v11
	v_exp_f32_e32 v13, v13
	v_exp_f32_e32 v10, v10
	v_exp_f32_e32 v18, v18
	v_exp_f32_e32 v11, v11
	v_add_f32_e32 v13, 1.0, v13
	v_add_f32_e32 v22, 1.0, v10
	v_add_f32_e32 v18, 1.0, v18
	v_add_f32_e32 v11, 1.0, v11
	v_rcp_f32_e32 v10, v13
	v_rcp_f32_e32 v18, v18
	v_rcp_f32_e32 v19, v11
	v_rcp_f32_e32 v11, v22
	v_pk_mul_f32 v[6:7], v[6:7], v[18:19]
	v_pk_mul_f32 v[4:5], v[4:5], v[10:11]
	v_pk_mul_f32 v[6:7], v[12:13], v[6:7] op_sel_hi:[0,1]
	v_pk_mul_f32 v[4:5], v[12:13], v[4:5] op_sel_hi:[0,1]
	s_waitcnt vmcnt(0)
	v_pk_mul_f32 v[6:7], v[16:17], v[6:7]
	v_pk_mul_f32 v[4:5], v[14:15], v[4:5]
	s_nop 0
	v_cvt_pk_bf16_f32 v4, v4, v5
	v_cvt_pk_bf16_f32 v5, v6, v7
	global_store_dwordx2 v[8:9], v[4:5], off offset:192
	v_mov_b32_e32 v10, v234
	v_mov_b32_e32 v11, v235
	s_nop 0
	global_load_dwordx4 v[4:7], v68, s[30:31] offset:448
	s_waitcnt vmcnt(1)
	v_lshlrev_b32_e32 v13, 16, v10
	v_and_b32_e32 v10, 0xffff0000, v10
	v_lshlrev_b32_e32 v14, 16, v11
	v_and_b32_e32 v11, 0xffff0000, v11
	v_mul_f32_e32 v13, 0xbfb8aa3b, v13
	v_mul_f32_e32 v10, 0xbfb8aa3b, v10
	v_mul_f32_e32 v14, 0xbfb8aa3b, v14
	v_mul_f32_e32 v11, 0xbfb8aa3b, v11
	v_exp_f32_e32 v13, v13
	v_exp_f32_e32 v10, v10
	v_exp_f32_e32 v14, v14
	v_exp_f32_e32 v11, v11
	v_add_f32_e32 v13, 1.0, v13
	v_add_f32_e32 v16, 1.0, v10
	v_add_f32_e32 v14, 1.0, v14
	v_add_f32_e32 v11, 1.0, v11
	v_rcp_f32_e32 v10, v13
	v_rcp_f32_e32 v14, v14
	v_rcp_f32_e32 v15, v11
	v_rcp_f32_e32 v11, v16
	v_pk_mul_f32 v[2:3], v[2:3], v[14:15]
	v_pk_mul_f32 v[0:1], v[0:1], v[10:11]
	v_pk_mul_f32 v[2:3], v[12:13], v[2:3] op_sel_hi:[0,1]
	v_pk_mul_f32 v[0:1], v[12:13], v[0:1] op_sel_hi:[0,1]
	s_waitcnt vmcnt(0)
	v_pk_mul_f32 v[2:3], v[6:7], v[2:3]
	v_pk_mul_f32 v[0:1], v[4:5], v[0:1]
	s_nop 0
	v_cvt_pk_bf16_f32 v0, v0, v1
	v_cvt_pk_bf16_f32 v1, v2, v3
	global_store_dwordx2 v[8:9], v[0:1], off offset:224
	s_cbranch_scc1 .LBB1_806
